# v30 + P3 mlstm_scan: all 32 UT loads of both batches issued before the CHS load and gate recurrence (batch 2 into spare VGPRs, copied at the old load site)
# speedup vs baseline: 1.0096x; 1.0052x over previous
.LBB0_948:
	s_cmp_lt_i32 s4, 4
	s_cselect_b64 s[0:1], -1, 0
	s_cmp_gt_i32 s5, 3
	s_cselect_b64 s[2:3], -1, 0
	s_and_b64 s[0:1], s[0:1], s[2:3]
	s_andn2_b64 vcc, exec, s[0:1]
	s_cbranch_vccnz .LBB0_1031
	s_waitcnt vmcnt(0)
	v_mov_b32_e32 v84, v0
	s_ashr_i32 s0, s92, 3
	s_and_b32 s14, s92, 7
	s_mov_b32 s10, s0
	s_ashr_i32 s11, s0, 31
	s_lshl_b64 s[12:13], s[10:11], 12
	v_ashrrev_i32_e32 v230, 4, v84
	v_lshlrev_b32_e32 v236, 4, v84
	v_mov_b32_e32 v237, 0
	v_lshl_add_u32 v232, s14, 5, v230
	v_and_b32_e32 v236, 0xf0, v236
	v_ashrrev_i32_e32 v233, 31, v232
	v_lshlrev_b32_e32 v236, 1, v236
	v_lshl_add_u64 v[234:235], s[12:13], 0, v[232:233]
	v_lshlrev_b64 v[234:235], 9, v[234:235]
	v_lshl_add_u64 v[234:235], s[96:97], 0, v[234:235]
	v_lshl_add_u64 v[238:239], v[234:235], 0, v[236:237]
	s_mov_b64 s[12:13], 0x23b80000
	v_lshl_add_u64 v[240:241], v[238:239], 0, s[12:13]
	global_load_dwordx4 v[78:81], v[240:241], off nt
	global_load_dwordx4 v[74:77], v[240:241], off offset:16 nt
	s_mov_b64 s[12:13], 0x23ba0000
	v_lshl_add_u64 v[242:243], v[238:239], 0, s[12:13]
	global_load_dwordx4 v[62:65], v[242:243], off nt
	global_load_dwordx4 v[50:53], v[242:243], off offset:16 nt
	s_mov_b64 s[12:13], 0x23bc0000
	v_lshl_add_u64 v[240:241], v[238:239], 0, s[12:13]
	global_load_dwordx4 v[46:49], v[240:241], off nt
	global_load_dwordx4 v[42:45], v[240:241], off offset:16 nt
	s_mov_b64 s[12:13], 0x23be0000
	v_lshl_add_u64 v[242:243], v[238:239], 0, s[12:13]
	global_load_dwordx4 v[38:41], v[242:243], off nt
	global_load_dwordx4 v[34:37], v[242:243], off offset:16 nt
	s_mov_b64 s[12:13], 0x23c00000
	v_lshl_add_u64 v[240:241], v[238:239], 0, s[12:13]
	global_load_dwordx4 v[30:33], v[240:241], off nt
	global_load_dwordx4 v[26:29], v[240:241], off offset:16 nt
	s_mov_b64 s[12:13], 0x23c20000
	v_lshl_add_u64 v[242:243], v[238:239], 0, s[12:13]
	global_load_dwordx4 v[22:25], v[242:243], off nt
	global_load_dwordx4 v[18:21], v[242:243], off offset:16 nt
	s_mov_b64 s[12:13], 0x23c40000
	v_lshl_add_u64 v[240:241], v[238:239], 0, s[12:13]
	global_load_dwordx4 v[14:17], v[240:241], off nt
	global_load_dwordx4 v[10:13], v[240:241], off offset:16 nt
	s_mov_b64 s[12:13], 0x23c60000
	v_lshl_add_u64 v[242:243], v[238:239], 0, s[12:13]
	global_load_dwordx4 v[6:9], v[242:243], off nt
	global_load_dwordx4 v[2:5], v[242:243], off offset:16 nt
	s_mov_b64 s[12:13], 0x23c80000
	v_lshl_add_u64 v[240:241], v[238:239], 0, s[12:13]
	global_load_dwordx4 v[110:113], v[240:241], off nt
	global_load_dwordx4 v[114:117], v[240:241], off offset:16 nt
	s_mov_b64 s[12:13], 0x23ca0000
	v_lshl_add_u64 v[242:243], v[238:239], 0, s[12:13]
	global_load_dwordx4 v[118:121], v[242:243], off nt
	global_load_dwordx4 v[122:125], v[242:243], off offset:16 nt
	s_mov_b64 s[12:13], 0x23cc0000
	v_lshl_add_u64 v[240:241], v[238:239], 0, s[12:13]
	global_load_dwordx4 v[126:129], v[240:241], off nt
	global_load_dwordx4 v[130:133], v[240:241], off offset:16 nt
	s_mov_b64 s[12:13], 0x23ce0000
	v_lshl_add_u64 v[242:243], v[238:239], 0, s[12:13]
	global_load_dwordx4 v[134:137], v[242:243], off nt
	global_load_dwordx4 v[138:141], v[242:243], off offset:16 nt
	s_mov_b64 s[12:13], 0x23d00000
	v_lshl_add_u64 v[240:241], v[238:239], 0, s[12:13]
	global_load_dwordx4 v[142:145], v[240:241], off nt
	global_load_dwordx4 v[146:149], v[240:241], off offset:16 nt
	s_mov_b64 s[12:13], 0x23d20000
	v_lshl_add_u64 v[242:243], v[238:239], 0, s[12:13]
	global_load_dwordx4 v[150:153], v[242:243], off nt
	global_load_dwordx4 v[154:157], v[242:243], off offset:16 nt
	s_mov_b64 s[12:13], 0x23d40000
	v_lshl_add_u64 v[240:241], v[238:239], 0, s[12:13]
	global_load_dwordx4 v[158:161], v[240:241], off nt
	global_load_dwordx4 v[162:165], v[240:241], off offset:16 nt
	s_mov_b64 s[12:13], 0x23d60000
	v_lshl_add_u64 v[242:243], v[238:239], 0, s[12:13]
	global_load_dwordx4 v[166:169], v[242:243], off nt
	global_load_dwordx4 v[170:173], v[242:243], off offset:16 nt
	s_nop 0
	v_cmp_gt_i32_e32 vcc, 32, v84
	v_lshl_add_u32 v201, v84, 2, 0
	v_lshl_add_u32 v210, s0, 5, v84
	s_and_saveexec_b64 s[2:3], vcc
	s_cbranch_execz .LBB0_951
	v_ashrrev_i32_e32 v211, 31, v210
	v_lshl_add_u64 v[202:203], v[210:211], 2, s[96:97]
	v_add_co_u32_e32 v202, vcc, 0x2bc80000, v202
	s_nop 1
	v_addc_co_u32_e32 v203, vcc, 0, v203, vcc
	global_load_dword v202, v[202:203], off
	s_waitcnt vmcnt(0)
	ds_write_b32 v201, v202 offset:256
.LBB0_951:
	s_or_b64 exec, exec, s[2:3]
	v_cmp_eq_u32_e32 vcc, 0, v84
	s_waitcnt lgkmcnt(0)
	s_barrier
	s_and_saveexec_b64 s[2:3], vcc
	s_cbranch_execz .LBB0_953
	v_mov_b32_e32 v202, 0
	ds_read_b128 v[212:215], v202 offset:256
	ds_read_b128 v[216:219], v202 offset:272
	s_mov_b32 s1, 0x3fb8aa3b
	s_mov_b32 s4, 0xc2ce8ed0
	s_mov_b32 s5, 0x42b17218
	s_waitcnt lgkmcnt(1)
	v_max_f32_e32 v203, v212, v212
	v_max_f32_e32 v203, 0, v203
	v_add_f32_e32 v204, 0, v213
	v_add_f32_e32 v203, v213, v203
	v_sub_f32_e32 v204, v204, v203
	v_mul_f32_e32 v205, 0x3fb8aa3b, v204
	v_fma_f32 v206, v204, s1, -v205
	v_rndne_f32_e32 v207, v205
	v_fmac_f32_e32 v206, 0x32a5705f, v204
	v_sub_f32_e32 v205, v205, v207
	v_add_f32_e32 v205, v205, v206
	v_exp_f32_e32 v205, v205
	v_cvt_i32_f32_e32 v211, v207
	v_cmp_ngt_f32_e32 vcc, s4, v204
	ds_read_b128 v[220:223], v202 offset:288
	ds_read_b128 v[206:209], v202 offset:304
	v_ldexp_f32 v205, v205, v211
	v_add_f32_e32 v211, v212, v213
	v_sub_f32_e32 v213, v211, v203
	v_mul_f32_e32 v211, 0x3fb8aa3b, v213
	v_fma_f32 v212, v213, s1, -v211
	v_rndne_f32_e32 v224, v211
	v_fmac_f32_e32 v212, 0x32a5705f, v213
	v_sub_f32_e32 v211, v211, v224
	v_add_f32_e32 v211, v211, v212
	v_exp_f32_e32 v225, v211
	v_cvt_i32_f32_e32 v224, v224
	v_cndmask_b32_e32 v205, 0, v205, vcc
	v_cmp_nlt_f32_e32 vcc, s5, v204
	v_max_f32_e32 v204, v214, v214
	v_mov_b32_e32 v211, 0x7f800000
	v_max_f32_e32 v204, v204, v203
	v_cndmask_b32_e32 v212, v211, v205, vcc
	v_ldexp_f32 v205, v225, v224
	v_add_f32_e32 v204, v215, v204
	v_add_f32_e32 v224, v203, v215
	v_sub_f32_e32 v225, v224, v204
	v_mul_f32_e32 v224, 0x3fb8aa3b, v225
	v_fma_f32 v226, v225, s1, -v224
	v_rndne_f32_e32 v227, v224
	v_fmac_f32_e32 v226, 0x32a5705f, v225
	v_sub_f32_e32 v224, v224, v227
	v_add_f32_e32 v224, v224, v226
	v_exp_f32_e32 v226, v224
	v_cvt_i32_f32_e32 v227, v227
	v_cmp_ngt_f32_e32 vcc, s4, v213
	s_nop 1
	v_cndmask_b32_e32 v205, 0, v205, vcc
	v_cmp_nlt_f32_e32 vcc, s5, v213
	v_add_f32_e32 v213, v214, v215
	v_sub_f32_e32 v214, v213, v204
	v_mul_f32_e32 v213, 0x3fb8aa3b, v214
	v_cndmask_b32_e32 v224, v211, v205, vcc
	v_ldexp_f32 v205, v226, v227
	v_fma_f32 v215, v214, s1, -v213
	v_rndne_f32_e32 v226, v213
	v_fmac_f32_e32 v215, 0x32a5705f, v214
	v_sub_f32_e32 v213, v213, v226
	v_add_f32_e32 v213, v213, v215
	v_cmp_ngt_f32_e32 vcc, s4, v225
	v_exp_f32_e32 v215, v213
	v_cvt_i32_f32_e32 v226, v226
	v_cndmask_b32_e32 v205, 0, v205, vcc
	v_cmp_nlt_f32_e32 vcc, s5, v225
	s_waitcnt lgkmcnt(2)
	v_add_f32_e32 v225, v204, v217
	v_ldexp_f32 v215, v215, v226
	v_cndmask_b32_e32 v213, v211, v205, vcc
	v_max_f32_e32 v205, v216, v216
	v_max_f32_e32 v205, v205, v204
	v_add_f32_e32 v205, v217, v205
	v_sub_f32_e32 v226, v225, v205
	v_mul_f32_e32 v225, 0x3fb8aa3b, v226
	v_fma_f32 v227, v226, s1, -v225
	v_rndne_f32_e32 v228, v225
	v_fmac_f32_e32 v227, 0x32a5705f, v226
	v_sub_f32_e32 v225, v225, v228
	v_add_f32_e32 v225, v225, v227
	v_cmp_ngt_f32_e32 vcc, s4, v214
	v_exp_f32_e32 v227, v225
	v_cvt_i32_f32_e32 v228, v228
	v_cndmask_b32_e32 v215, 0, v215, vcc
	v_cmp_nlt_f32_e32 vcc, s5, v214
	ds_write_b128 v202, v[202:205] offset:128
	v_ldexp_f32 v214, v227, v228
	v_cndmask_b32_e32 v225, v211, v215, vcc
	v_add_f32_e32 v215, v216, v217
	v_sub_f32_e32 v215, v215, v205
	v_mul_f32_e32 v216, 0x3fb8aa3b, v215
	v_fma_f32 v217, v215, s1, -v216
	v_rndne_f32_e32 v227, v216
	v_fmac_f32_e32 v217, 0x32a5705f, v215
	v_sub_f32_e32 v216, v216, v227
	v_add_f32_e32 v216, v216, v217
	v_exp_f32_e32 v216, v216
	v_cvt_i32_f32_e32 v217, v227
	v_cmp_ngt_f32_e32 vcc, s4, v226
	v_add_f32_e32 v204, v218, v219
	v_ldexp_f32 v216, v216, v217
	v_cndmask_b32_e32 v214, 0, v214, vcc
	v_cmp_nlt_f32_e32 vcc, s5, v226
	v_add_f32_e32 v226, v205, v219
	s_nop 0
	v_cndmask_b32_e32 v214, v211, v214, vcc
	v_cmp_ngt_f32_e32 vcc, s4, v215
	s_nop 1
	v_cndmask_b32_e32 v217, 0, v216, vcc
	v_max_f32_e32 v216, v218, v218
	v_max_f32_e32 v216, v216, v205
	v_add_f32_e32 v216, v219, v216
	v_sub_f32_e32 v227, v226, v216
	v_mul_f32_e32 v226, 0x3fb8aa3b, v227
	v_fma_f32 v228, v227, s1, -v226
	v_rndne_f32_e32 v229, v226
	v_fmac_f32_e32 v228, 0x32a5705f, v227
	v_sub_f32_e32 v226, v226, v229
	v_sub_f32_e32 v204, v204, v216
	v_add_f32_e32 v226, v226, v228
	v_cmp_nlt_f32_e32 vcc, s5, v215
	v_mul_f32_e32 v205, 0x3fb8aa3b, v204
	v_exp_f32_e32 v228, v226
	v_cndmask_b32_e32 v226, v211, v217, vcc
	v_fma_f32 v215, v204, s1, -v205
	v_rndne_f32_e32 v217, v205
	v_cvt_i32_f32_e32 v229, v229
	v_fmac_f32_e32 v215, 0x32a5705f, v204
	v_sub_f32_e32 v205, v205, v217
	v_add_f32_e32 v205, v205, v215
	v_exp_f32_e32 v205, v205
	v_cvt_i32_f32_e32 v217, v217
	v_ldexp_f32 v203, v228, v229
	v_cmp_ngt_f32_e32 vcc, s4, v227
	s_nop 1
	v_cndmask_b32_e32 v203, 0, v203, vcc
	v_cmp_nlt_f32_e32 vcc, s5, v227
	s_nop 1
	v_cndmask_b32_e32 v215, v211, v203, vcc
	v_ldexp_f32 v203, v205, v217
	s_waitcnt lgkmcnt(2)
	v_max_f32_e32 v205, v220, v220
	v_max_f32_e32 v205, v205, v216
	v_add_f32_e32 v217, v221, v205
	v_add_f32_e32 v205, v216, v221
	v_sub_f32_e32 v205, v205, v217
	ds_write_b128 v202, v[212:215]
	v_mul_f32_e32 v212, 0x3fb8aa3b, v205
	v_fma_f32 v213, v205, s1, -v212
	v_rndne_f32_e32 v214, v212
	v_fmac_f32_e32 v213, 0x32a5705f, v205
	v_sub_f32_e32 v212, v212, v214
	v_add_f32_e32 v212, v212, v213
	v_exp_f32_e32 v212, v212
	v_cvt_i32_f32_e32 v213, v214
	v_cmp_ngt_f32_e32 vcc, s4, v204
	s_nop 1
	v_cndmask_b32_e32 v203, 0, v203, vcc
	v_cmp_nlt_f32_e32 vcc, s5, v204
	v_add_f32_e32 v204, v220, v221
	v_sub_f32_e32 v204, v204, v217
	v_cndmask_b32_e32 v227, v211, v203, vcc
	v_ldexp_f32 v203, v212, v213
	v_mul_f32_e32 v212, 0x3fb8aa3b, v204
	v_fma_f32 v213, v204, s1, -v212
	v_rndne_f32_e32 v214, v212
	v_fmac_f32_e32 v213, 0x32a5705f, v204
	v_sub_f32_e32 v212, v212, v214
	v_add_f32_e32 v212, v212, v213
	v_cmp_ngt_f32_e32 vcc, s4, v205
	v_exp_f32_e32 v213, v212
	v_cvt_i32_f32_e32 v214, v214
	v_cndmask_b32_e32 v203, 0, v203, vcc
	v_cmp_nlt_f32_e32 vcc, s5, v205
	v_max_f32_e32 v205, v222, v222
	v_max_f32_e32 v205, v205, v217
	v_add_f32_e32 v218, v223, v205
	v_add_f32_e32 v205, v217, v223
	v_sub_f32_e32 v205, v205, v218
	v_cndmask_b32_e32 v212, v211, v203, vcc
	v_ldexp_f32 v203, v213, v214
	v_mul_f32_e32 v213, 0x3fb8aa3b, v205
	v_fma_f32 v214, v205, s1, -v213
	v_rndne_f32_e32 v215, v213
	v_fmac_f32_e32 v214, 0x32a5705f, v205
	v_sub_f32_e32 v213, v213, v215
	v_add_f32_e32 v213, v213, v214
	v_exp_f32_e32 v213, v213
	v_cvt_i32_f32_e32 v214, v215
	v_cmp_ngt_f32_e32 vcc, s4, v204
	ds_write_b128 v202, v[224:227] offset:64
	s_nop 0
	v_cndmask_b32_e32 v203, 0, v203, vcc
	v_cmp_nlt_f32_e32 vcc, s5, v204
	v_add_f32_e32 v204, v222, v223
	v_sub_f32_e32 v204, v204, v218
	v_cndmask_b32_e32 v220, v211, v203, vcc
	v_ldexp_f32 v203, v213, v214
	v_mul_f32_e32 v213, 0x3fb8aa3b, v204
	v_fma_f32 v214, v204, s1, -v213
	v_rndne_f32_e32 v215, v213
	v_fmac_f32_e32 v214, 0x32a5705f, v204
	v_sub_f32_e32 v213, v213, v215
	v_add_f32_e32 v213, v213, v214
	v_cmp_ngt_f32_e32 vcc, s4, v205
	v_exp_f32_e32 v214, v213
	v_cvt_i32_f32_e32 v215, v215
	v_cndmask_b32_e32 v203, 0, v203, vcc
	v_cmp_nlt_f32_e32 vcc, s5, v205
	s_waitcnt lgkmcnt(3)
	v_max_f32_e32 v205, v206, v206
	v_max_f32_e32 v205, v205, v218
	v_add_f32_e32 v219, v207, v205
	v_add_f32_e32 v205, v218, v207
	v_sub_f32_e32 v205, v205, v219
	v_cndmask_b32_e32 v213, v211, v203, vcc
	v_ldexp_f32 v203, v214, v215
	v_mul_f32_e32 v214, 0x3fb8aa3b, v205
	v_fma_f32 v215, v205, s1, -v214
	v_rndne_f32_e32 v221, v214
	v_fmac_f32_e32 v215, 0x32a5705f, v205
	v_sub_f32_e32 v214, v214, v221
	v_add_f32_e32 v214, v214, v215
	v_exp_f32_e32 v214, v214
	v_cvt_i32_f32_e32 v215, v221
	v_cmp_ngt_f32_e32 vcc, s4, v204
	ds_write_b128 v202, v[216:219] offset:144
	s_nop 0
	v_cndmask_b32_e32 v203, 0, v203, vcc
	v_cmp_nlt_f32_e32 vcc, s5, v204
	v_add_f32_e32 v204, v206, v207
	v_sub_f32_e32 v204, v204, v219
	v_mul_f32_e32 v206, 0x3fb8aa3b, v204
	v_cndmask_b32_e32 v221, v211, v203, vcc
	v_ldexp_f32 v203, v214, v215
	v_fma_f32 v207, v204, s1, -v206
	v_rndne_f32_e32 v214, v206
	v_fmac_f32_e32 v207, 0x32a5705f, v204
	v_sub_f32_e32 v206, v206, v214
	v_add_f32_e32 v206, v206, v207
	v_exp_f32_e32 v206, v206
	v_cvt_i32_f32_e32 v207, v214
	v_cmp_ngt_f32_e32 vcc, s4, v205
	s_nop 1
	v_cndmask_b32_e32 v203, 0, v203, vcc
	v_cmp_nlt_f32_e32 vcc, s5, v205
	v_max_f32_e32 v205, v208, v208
	v_max_f32_e32 v205, v205, v219
	v_cndmask_b32_e32 v214, v211, v203, vcc
	v_ldexp_f32 v203, v206, v207
	v_add_f32_e32 v206, v209, v205
	v_add_f32_e32 v205, v219, v209
	v_sub_f32_e32 v205, v205, v206
	v_mul_f32_e32 v207, 0x3fb8aa3b, v205
	v_fma_f32 v215, v205, s1, -v207
	v_rndne_f32_e32 v222, v207
	v_fmac_f32_e32 v215, 0x32a5705f, v205
	v_sub_f32_e32 v207, v207, v222
	v_add_f32_e32 v207, v207, v215
	v_exp_f32_e32 v207, v207
	v_cvt_i32_f32_e32 v215, v222
	v_cmp_ngt_f32_e32 vcc, s4, v204
	ds_read_b128 v[216:219], v202 offset:336
	s_nop 0
	v_cndmask_b32_e32 v203, 0, v203, vcc
	v_cmp_nlt_f32_e32 vcc, s5, v204
	v_add_f32_e32 v204, v208, v209
	v_sub_f32_e32 v204, v204, v206
	v_cndmask_b32_e32 v222, v211, v203, vcc
	v_ldexp_f32 v203, v207, v215
	v_cmp_ngt_f32_e32 vcc, s4, v205
	v_mul_f32_e32 v207, 0x3fb8aa3b, v204
	v_fma_f32 v208, v204, s1, -v207
	v_cndmask_b32_e32 v203, 0, v203, vcc
	v_cmp_nlt_f32_e32 vcc, s5, v205
	v_rndne_f32_e32 v209, v207
	v_fmac_f32_e32 v208, 0x32a5705f, v204
	v_cndmask_b32_e32 v215, v211, v203, vcc
	ds_write_b128 v202, v[212:215] offset:16
	ds_read_b128 v[212:215], v202 offset:320
	v_sub_f32_e32 v207, v207, v209
	v_add_f32_e32 v207, v207, v208
	v_exp_f32_e32 v207, v207
	v_cvt_i32_f32_e32 v208, v209
	s_waitcnt lgkmcnt(0)
	v_max_f32_e32 v205, v212, v212
	v_max_f32_e32 v205, v205, v206
	v_cmp_ngt_f32_e32 vcc, s4, v204
	v_ldexp_f32 v203, v207, v208
	v_add_f32_e32 v207, v213, v205
	v_add_f32_e32 v205, v206, v213
	v_sub_f32_e32 v205, v205, v207
	v_mul_f32_e32 v208, 0x3fb8aa3b, v205
	v_fma_f32 v209, v205, s1, -v208
	v_rndne_f32_e32 v223, v208
	v_fmac_f32_e32 v209, 0x32a5705f, v205
	v_sub_f32_e32 v208, v208, v223
	v_add_f32_e32 v208, v208, v209
	v_exp_f32_e32 v208, v208
	v_cvt_i32_f32_e32 v209, v223
	v_cndmask_b32_e32 v203, 0, v203, vcc
	v_cmp_nlt_f32_e32 vcc, s5, v204
	v_add_f32_e32 v204, v212, v213
	v_sub_f32_e32 v204, v204, v207
	v_cndmask_b32_e32 v223, v211, v203, vcc
	v_ldexp_f32 v203, v208, v209
	v_mul_f32_e32 v208, 0x3fb8aa3b, v204
	v_fma_f32 v209, v204, s1, -v208
	v_rndne_f32_e32 v212, v208
	v_fmac_f32_e32 v209, 0x32a5705f, v204
	v_sub_f32_e32 v208, v208, v212
	v_add_f32_e32 v208, v208, v209
	v_exp_f32_e32 v208, v208
	v_cvt_i32_f32_e32 v209, v212
	v_cmp_ngt_f32_e32 vcc, s4, v205
	ds_write_b128 v202, v[220:223] offset:80
	s_nop 0
	v_cndmask_b32_e32 v203, 0, v203, vcc
	v_cmp_nlt_f32_e32 vcc, s5, v205
	v_max_f32_e32 v205, v214, v214
	v_max_f32_e32 v205, v205, v207
	v_cndmask_b32_e32 v212, v211, v203, vcc
	v_ldexp_f32 v203, v208, v209
	v_add_f32_e32 v208, v215, v205
	v_add_f32_e32 v205, v207, v215
	v_sub_f32_e32 v205, v205, v208
	v_mul_f32_e32 v209, 0x3fb8aa3b, v205
	v_fma_f32 v213, v205, s1, -v209
	v_rndne_f32_e32 v220, v209
	v_fmac_f32_e32 v213, 0x32a5705f, v205
	v_sub_f32_e32 v209, v209, v220
	v_add_f32_e32 v209, v209, v213
	v_exp_f32_e32 v209, v209
	v_cvt_i32_f32_e32 v213, v220
	v_cmp_ngt_f32_e32 vcc, s4, v204
	s_nop 1
	v_cndmask_b32_e32 v203, 0, v203, vcc
	v_cmp_nlt_f32_e32 vcc, s5, v204
	v_add_f32_e32 v204, v214, v215
	v_sub_f32_e32 v204, v204, v208
	v_cndmask_b32_e32 v220, v211, v203, vcc
	v_ldexp_f32 v203, v209, v213
	v_mul_f32_e32 v209, 0x3fb8aa3b, v204
	v_fma_f32 v213, v204, s1, -v209
	v_rndne_f32_e32 v214, v209
	v_fmac_f32_e32 v213, 0x32a5705f, v204
	v_sub_f32_e32 v209, v209, v214
	v_add_f32_e32 v209, v209, v213
	v_exp_f32_e32 v209, v209
	v_cvt_i32_f32_e32 v214, v214
	v_cmp_ngt_f32_e32 vcc, s4, v205
	s_nop 1
	v_cndmask_b32_e32 v203, 0, v203, vcc
	v_cmp_nlt_f32_e32 vcc, s5, v205
	v_max_f32_e32 v205, v216, v216
	v_max_f32_e32 v205, v205, v208
	v_cndmask_b32_e32 v213, v211, v203, vcc
	v_ldexp_f32 v203, v209, v214
	v_add_f32_e32 v209, v217, v205
	v_add_f32_e32 v205, v208, v217
	v_sub_f32_e32 v205, v205, v209
	v_mul_f32_e32 v214, 0x3fb8aa3b, v205
	v_fma_f32 v215, v205, s1, -v214
	v_rndne_f32_e32 v221, v214
	v_fmac_f32_e32 v215, 0x32a5705f, v205
	v_sub_f32_e32 v214, v214, v221
	v_add_f32_e32 v214, v214, v215
	v_exp_f32_e32 v214, v214
	v_cvt_i32_f32_e32 v215, v221
	v_cmp_ngt_f32_e32 vcc, s4, v204
	ds_write_b128 v202, v[206:209] offset:160
	v_add_f32_e32 v206, v218, v219
	v_cndmask_b32_e32 v203, 0, v203, vcc
	v_cmp_nlt_f32_e32 vcc, s5, v204
	v_add_f32_e32 v204, v216, v217
	s_nop 0
	v_cndmask_b32_e32 v221, v211, v203, vcc
	v_ldexp_f32 v203, v214, v215
	v_sub_f32_e32 v215, v204, v209
	v_mul_f32_e32 v204, 0x3fb8aa3b, v215
	v_fma_f32 v214, v215, s1, -v204
	v_rndne_f32_e32 v216, v204
	v_fmac_f32_e32 v214, 0x32a5705f, v215
	v_sub_f32_e32 v204, v204, v216
	v_add_f32_e32 v204, v204, v214
	v_exp_f32_e32 v204, v204
	v_cvt_i32_f32_e32 v216, v216
	v_cmp_ngt_f32_e32 vcc, s4, v205
	s_nop 1
	v_cndmask_b32_e32 v203, 0, v203, vcc
	v_cmp_nlt_f32_e32 vcc, s5, v205
	v_add_f32_e32 v205, v209, v219
	s_nop 0
	v_cndmask_b32_e32 v214, v211, v203, vcc
	v_ldexp_f32 v203, v204, v216
	v_max_f32_e32 v204, v218, v218
	v_max_f32_e32 v204, v204, v209
	v_add_f32_e32 v204, v219, v204
	v_sub_f32_e32 v205, v205, v204
	v_mul_f32_e32 v216, 0x3fb8aa3b, v205
	v_fma_f32 v217, v205, s1, -v216
	v_rndne_f32_e32 v222, v216
	v_fmac_f32_e32 v217, 0x32a5705f, v205
	v_sub_f32_e32 v216, v216, v222
	v_add_f32_e32 v216, v216, v217
	v_exp_f32_e32 v216, v216
	v_cvt_i32_f32_e32 v217, v222
	v_cmp_ngt_f32_e32 vcc, s4, v215
	s_nop 1
	v_cndmask_b32_e32 v203, 0, v203, vcc
	v_cmp_nlt_f32_e32 vcc, s5, v215
	s_nop 1
	v_cndmask_b32_e32 v222, v211, v203, vcc
	v_ldexp_f32 v203, v216, v217
	v_sub_f32_e32 v216, v206, v204
	v_mul_f32_e32 v206, 0x3fb8aa3b, v216
	v_fma_f32 v207, v216, s1, -v206
	v_rndne_f32_e32 v208, v206
	v_fmac_f32_e32 v207, 0x32a5705f, v216
	v_sub_f32_e32 v206, v206, v208
	v_add_f32_e32 v206, v206, v207
	v_exp_f32_e32 v217, v206
	v_cvt_i32_f32_e32 v218, v208
	ds_read_b128 v[206:209], v202 offset:352
	v_cmp_ngt_f32_e32 vcc, s4, v205
	s_nop 1
	v_cndmask_b32_e32 v203, 0, v203, vcc
	v_cmp_nlt_f32_e32 vcc, s5, v205
	s_nop 1
	v_cndmask_b32_e32 v215, v211, v203, vcc
	ds_write_b128 v202, v[212:215] offset:32
	ds_read_b128 v[212:215], v202 offset:368
	s_waitcnt lgkmcnt(2)
	v_max_f32_e32 v205, v206, v206
	v_max_f32_e32 v205, v205, v204
	v_ldexp_f32 v203, v217, v218
	v_add_f32_e32 v205, v207, v205
	v_add_f32_e32 v217, v204, v207
	v_sub_f32_e32 v217, v217, v205
	v_mul_f32_e32 v218, 0x3fb8aa3b, v217
	v_fma_f32 v219, v217, s1, -v218
	v_rndne_f32_e32 v223, v218
	v_fmac_f32_e32 v219, 0x32a5705f, v217
	v_sub_f32_e32 v218, v218, v223
	v_add_f32_e32 v218, v218, v219
	v_exp_f32_e32 v218, v218
	v_cvt_i32_f32_e32 v219, v223
	v_add_f32_e32 v206, v206, v207
	v_cmp_ngt_f32_e32 vcc, s4, v216
	v_sub_f32_e32 v207, v206, v205
	v_mul_f32_e32 v206, 0x3fb8aa3b, v207
	v_cndmask_b32_e32 v203, 0, v203, vcc
	v_cmp_nlt_f32_e32 vcc, s5, v216
	v_fma_f32 v216, v207, s1, -v206
	v_fmac_f32_e32 v216, 0x32a5705f, v207
	v_cndmask_b32_e32 v223, v211, v203, vcc
	v_ldexp_f32 v203, v218, v219
	v_rndne_f32_e32 v218, v206
	v_sub_f32_e32 v206, v206, v218
	v_add_f32_e32 v206, v206, v216
	v_exp_f32_e32 v206, v206
	v_cvt_i32_f32_e32 v218, v218
	v_cmp_ngt_f32_e32 vcc, s4, v217
	ds_write_b128 v202, v[220:223] offset:96
	s_nop 0
	v_cndmask_b32_e32 v203, 0, v203, vcc
	v_cmp_nlt_f32_e32 vcc, s5, v217
	v_add_f32_e32 v217, v205, v209
	s_nop 0
	v_cndmask_b32_e32 v216, v211, v203, vcc
	v_ldexp_f32 v203, v206, v218
	v_max_f32_e32 v206, v208, v208
	v_max_f32_e32 v206, v206, v205
	v_add_f32_e32 v206, v209, v206
	v_sub_f32_e32 v217, v217, v206
	v_mul_f32_e32 v218, 0x3fb8aa3b, v217
	v_fma_f32 v219, v217, s1, -v218
	v_rndne_f32_e32 v220, v218
	v_fmac_f32_e32 v219, 0x32a5705f, v217
	v_sub_f32_e32 v218, v218, v220
	v_add_f32_e32 v218, v218, v219
	v_exp_f32_e32 v218, v218
	v_cvt_i32_f32_e32 v219, v220
	v_cmp_ngt_f32_e32 vcc, s4, v207
	s_nop 1
	v_cndmask_b32_e32 v203, 0, v203, vcc
	v_cmp_nlt_f32_e32 vcc, s5, v207
	v_add_f32_e32 v207, v208, v209
	v_sub_f32_e32 v208, v207, v206
	v_mul_f32_e32 v207, 0x3fb8aa3b, v208
	v_cndmask_b32_e32 v220, v211, v203, vcc
	v_ldexp_f32 v203, v218, v219
	v_fma_f32 v209, v208, s1, -v207
	v_rndne_f32_e32 v218, v207
	v_fmac_f32_e32 v209, 0x32a5705f, v208
	v_sub_f32_e32 v207, v207, v218
	v_add_f32_e32 v207, v207, v209
	v_exp_f32_e32 v207, v207
	v_cvt_i32_f32_e32 v209, v218
	v_cmp_ngt_f32_e32 vcc, s4, v217
	s_nop 1
	v_cndmask_b32_e32 v203, 0, v203, vcc
	v_cmp_nlt_f32_e32 vcc, s5, v217
	s_nop 1
	v_cndmask_b32_e32 v217, v211, v203, vcc
	v_ldexp_f32 v203, v207, v209
	s_waitcnt lgkmcnt(1)
	v_max_f32_e32 v207, v212, v212
	v_max_f32_e32 v207, v207, v206
	v_add_f32_e32 v207, v213, v207
	v_add_f32_e32 v209, v206, v213
	v_sub_f32_e32 v209, v209, v207
	v_mul_f32_e32 v218, 0x3fb8aa3b, v209
	v_fma_f32 v219, v209, s1, -v218
	v_rndne_f32_e32 v221, v218
	v_fmac_f32_e32 v219, 0x32a5705f, v209
	v_sub_f32_e32 v218, v218, v221
	v_add_f32_e32 v218, v218, v219
	v_exp_f32_e32 v218, v218
	v_cvt_i32_f32_e32 v219, v221
	v_cmp_ngt_f32_e32 vcc, s4, v208
	ds_write_b128 v202, v[204:207] offset:176
	v_add_f32_e32 v204, v214, v215
	v_cndmask_b32_e32 v203, 0, v203, vcc
	v_cmp_nlt_f32_e32 vcc, s5, v208
	v_add_f32_e32 v208, v212, v213
	v_sub_f32_e32 v208, v208, v207
	v_mul_f32_e32 v212, 0x3fb8aa3b, v208
	v_cndmask_b32_e32 v221, v211, v203, vcc
	v_ldexp_f32 v203, v218, v219
	v_fma_f32 v213, v208, s1, -v212
	v_rndne_f32_e32 v218, v212
	v_fmac_f32_e32 v213, 0x32a5705f, v208
	v_sub_f32_e32 v212, v212, v218
	v_add_f32_e32 v212, v212, v213
	v_exp_f32_e32 v212, v212
	v_cvt_i32_f32_e32 v213, v218
	v_cmp_ngt_f32_e32 vcc, s4, v209
	s_nop 1
	v_cndmask_b32_e32 v203, 0, v203, vcc
	v_cmp_nlt_f32_e32 vcc, s5, v209
	v_max_f32_e32 v209, v214, v214
	v_max_f32_e32 v209, v209, v207
	v_cndmask_b32_e32 v218, v211, v203, vcc
	v_ldexp_f32 v203, v212, v213
	v_add_f32_e32 v209, v215, v209
	v_add_f32_e32 v212, v207, v215
	v_sub_f32_e32 v212, v212, v209
	v_mul_f32_e32 v213, 0x3fb8aa3b, v212
	v_fma_f32 v219, v212, s1, -v213
	v_rndne_f32_e32 v222, v213
	v_sub_f32_e32 v204, v204, v209
	v_fmac_f32_e32 v219, 0x32a5705f, v212
	v_sub_f32_e32 v213, v213, v222
	v_mul_f32_e32 v205, 0x3fb8aa3b, v204
	v_add_f32_e32 v213, v213, v219
	v_fma_f32 v206, v204, s1, -v205
	v_rndne_f32_e32 v207, v205
	v_exp_f32_e32 v213, v213
	v_cvt_i32_f32_e32 v219, v222
	v_fmac_f32_e32 v206, 0x32a5705f, v204
	v_sub_f32_e32 v205, v205, v207
	v_add_f32_e32 v205, v205, v206
	v_cmp_ngt_f32_e32 vcc, s4, v208
	v_exp_f32_e32 v205, v205
	v_cvt_i32_f32_e32 v206, v207
	v_cndmask_b32_e32 v203, 0, v203, vcc
	v_cmp_nlt_f32_e32 vcc, s5, v208
	s_nop 1
	v_cndmask_b32_e32 v222, v211, v203, vcc
	v_ldexp_f32 v203, v213, v219
	v_cmp_ngt_f32_e32 vcc, s4, v212
	s_nop 1
	v_cndmask_b32_e32 v203, 0, v203, vcc
	v_cmp_nlt_f32_e32 vcc, s5, v212
	s_nop 1
	v_cndmask_b32_e32 v219, v211, v203, vcc
	v_ldexp_f32 v203, v205, v206
	v_cmp_ngt_f32_e32 vcc, s4, v204
	ds_write_b128 v202, v[216:219] offset:48
	s_nop 0
	v_cndmask_b32_e32 v203, 0, v203, vcc
	v_cmp_nlt_f32_e32 vcc, s5, v204
	s_nop 1
	v_cndmask_b32_e32 v223, v211, v203, vcc
	ds_write_b128 v202, v[220:223] offset:112
	ds_write_b32 v202, v209 offset:192
.LBB0_953:
	s_or_b64 exec, exec, s[2:3]
	s_and_b32 s6, s92, 7
	s_cmp_eq_u32 s6, 0
	s_cselect_b64 s[2:3], -1, 0
	v_cmp_gt_i32_e32 vcc, 17, v84
	s_and_b64 s[8:9], s[2:3], vcc
	s_waitcnt lgkmcnt(0)
	s_barrier
	s_and_saveexec_b64 s[4:5], s[8:9]
	s_cbranch_execz .LBB0_956
	ds_read_b32 v201, v201 offset:128
	v_ashrrev_i32_e32 v211, 31, v210
	v_lshl_add_u64 v[202:203], v[210:211], 2, s[96:97]
	v_add_co_u32_e32 v202, vcc, 0x2bc81000, v202
	s_nop 1
	v_addc_co_u32_e32 v203, vcc, 0, v203, vcc
	v_cmp_eq_u32_e32 vcc, 16, v84
	s_waitcnt lgkmcnt(0)
	global_store_dword v[202:203], v201, off
	s_and_b64 exec, exec, vcc
	s_cbranch_execz .LBB0_956
	v_mov_b32_e32 v201, 0
	ds_read_b32 v201, v201 offset:192
	s_ashr_i32 s1, s0, 31
	v_readlane_b32 s12, v245, 25
	s_lshl_b64 s[8:9], s[0:1], 2
	v_readlane_b32 s26, v245, 39
	v_readlane_b32 s27, v245, 40
	s_add_u32 s8, s26, s8
	s_addc_u32 s9, s27, s9
	v_mov_b32_e32 v202, 0x4888000
	v_readlane_b32 s13, v245, 26
	v_readlane_b32 s14, v245, 27
	v_readlane_b32 s15, v245, 28
	v_readlane_b32 s16, v245, 29
	v_readlane_b32 s17, v245, 30
	v_readlane_b32 s18, v245, 31
	v_readlane_b32 s19, v245, 32
	v_readlane_b32 s20, v245, 33
	v_readlane_b32 s21, v245, 34
	v_readlane_b32 s22, v245, 35
	v_readlane_b32 s23, v245, 36
	v_readlane_b32 s24, v245, 37
	v_readlane_b32 s25, v245, 38
	s_waitcnt lgkmcnt(0)
	global_store_dword v202, v201, s[8:9]
.LBB0_956:
	s_or_b64 exec, exec, s[4:5]
	v_ashrrev_i32_e32 v1, 4, v84
	v_lshl_add_u32 v232, s6, 5, v1
	v_lshlrev_b32_e32 v233, 4, v84
	s_ashr_i32 s1, s0, 31
	v_and_b32_e32 v85, 0xf0, v233
	s_lshl_b64 s[4:5], s[0:1], 12
	v_ashrrev_i32_e32 v233, 31, v232
	v_lshl_add_u64 v[234:235], s[4:5], 0, v[232:233]
	v_lshlrev_b64 v[234:235], 9, v[234:235]
	v_ashrrev_i32_e32 v232, 1, v232
	s_lshl_b64 s[8:9], s[0:1], 21
	v_bfi_b32 v232, -16, v232, v84
	v_lshl_add_u64 v[234:235], s[96:97], 0, v[234:235]
	v_lshlrev_b32_e32 v82, 1, v85
	v_mov_b32_e32 v83, 0
	s_add_u32 s8, s96, s8
	v_ashrrev_i32_e32 v233, 31, v232
	v_lshl_add_u64 v[88:89], v[234:235], 0, v[82:83]
	s_mov_b32 s7, 0x23b80000
	s_addc_u32 s9, s97, s9
	v_lshlrev_b64 v[232:233], 10, v[232:233]
	v_add_co_u32_e32 v234, vcc, s7, v88
	v_lshl_add_u64 v[232:233], s[8:9], 0, v[232:233]
	s_nop 0
	v_addc_co_u32_e32 v235, vcc, 0, v89, vcc
	s_mov_b64 s[8:9], 0x23b80000
	v_lshl_add_u64 v[234:235], v[88:89], 0, s[8:9]
	s_mov_b32 s7, 0x23ba0000
	v_add_co_u32_e32 v234, vcc, s7, v88
	v_and_b32_e32 v82, 0x1f0, v84
	s_mov_b64 s[8:9], 0x23ba0000
	v_addc_co_u32_e32 v235, vcc, 0, v89, vcc
	v_lshl_add_u64 v[86:87], v[232:233], 0, v[82:83]
	v_lshl_add_u64 v[232:233], v[88:89], 0, s[8:9]
	s_mov_b32 s7, 0x23bc0000
	v_add_co_u32_e32 v234, vcc, s7, v88
	s_mov_b64 s[8:9], 0x23bc0000
	s_nop 0
	v_addc_co_u32_e32 v235, vcc, 0, v89, vcc
	v_lshl_add_u64 v[232:233], v[88:89], 0, s[8:9]
	s_mov_b32 s7, 0x23be0000
	v_add_co_u32_e32 v234, vcc, s7, v88
	s_mov_b64 s[8:9], 0x23be0000
	s_nop 0
	v_addc_co_u32_e32 v235, vcc, 0, v89, vcc
	v_lshl_add_u64 v[232:233], v[88:89], 0, s[8:9]
	s_mov_b32 s7, 0x23c00000
	v_add_co_u32_e32 v234, vcc, s7, v88
	s_mov_b64 s[8:9], 0x23c00000
	s_nop 0
	v_addc_co_u32_e32 v235, vcc, 0, v89, vcc
	v_lshl_add_u64 v[232:233], v[88:89], 0, s[8:9]
	s_mov_b32 s7, 0x23c20000
	v_add_co_u32_e32 v234, vcc, s7, v88
	s_mov_b64 s[8:9], 0x23c20000
	s_nop 0
	v_addc_co_u32_e32 v235, vcc, 0, v89, vcc
	v_lshl_add_u64 v[232:233], v[88:89], 0, s[8:9]
	s_mov_b32 s7, 0x23c40000
	v_add_co_u32_e32 v234, vcc, s7, v88
	s_mov_b64 s[8:9], 0x23c40000
	s_nop 0
	v_addc_co_u32_e32 v235, vcc, 0, v89, vcc
	v_lshl_add_u64 v[232:233], v[88:89], 0, s[8:9]
	s_mov_b32 s7, 0x23c60000
	v_add_co_u32_e32 v240, vcc, s7, v88
	s_mov_b64 s[8:9], 0x23c60000
	s_nop 0
	v_addc_co_u32_e32 v241, vcc, 0, v89, vcc
	v_lshl_add_u64 v[242:243], v[88:89], 0, s[8:9]
	ds_read_b128 v[54:57], v83
	ds_read_b128 v[58:61], v83 offset:64
	ds_read_b128 v[66:69], v83 offset:16
	s_mov_b32 s7, 0x27ba0000
	v_add_co_u32_e32 v102, vcc, s7, v86
	s_waitcnt lgkmcnt(2)
	v_mul_f32_e32 v82, 0, v54
	v_addc_co_u32_e32 v103, vcc, 0, v87, vcc
	s_mov_b32 s7, 0x27bc0000
	ds_read_b128 v[70:73], v83 offset:80
	s_mov_b64 s[8:9], 0x23c80000
	v_lshlrev_b32_e32 v1, 2, v1
	v_readlane_b32 s36, v245, 25
	v_readlane_b32 s50, v245, 39
	v_readlane_b32 s51, v245, 40
	s_movk_i32 s10, 0x84
	v_readlane_b32 s37, v245, 26
	v_readlane_b32 s38, v245, 27
	v_readlane_b32 s39, v245, 28
	s_waitcnt vmcnt(15)
	v_lshlrev_b32_e32 v90, 16, v78
	v_and_b32_e32 v91, 0xffff0000, v78
	s_waitcnt vmcnt(14)
	v_lshlrev_b32_e32 v94, 16, v74
	v_and_b32_e32 v95, 0xffff0000, v74
	v_lshlrev_b32_e32 v74, 16, v75
	v_and_b32_e32 v75, 0xffff0000, v75
	v_lshlrev_b32_e32 v78, 16, v79
	v_and_b32_e32 v79, 0xffff0000, v79
	v_lshlrev_b32_e32 v92, 16, v80
	v_and_b32_e32 v93, 0xffff0000, v80
	v_lshlrev_b32_e32 v80, 16, v81
	v_and_b32_e32 v81, 0xffff0000, v81
	s_waitcnt lgkmcnt(2)
	v_pk_fma_f32 v[96:97], v[58:59], v[74:75], v[82:83] op_sel_hi:[0,1,0]
	v_lshlrev_b32_e32 v74, 16, v76
	v_and_b32_e32 v75, 0xffff0000, v76
	v_pk_fma_f32 v[90:91], v[58:59], v[90:91], v[82:83] op_sel_hi:[0,1,0]
	v_pk_fma_f32 v[78:79], v[58:59], v[78:79], v[82:83] op_sel_hi:[0,1,0]
	v_pk_fma_f32 v[92:93], v[58:59], v[92:93], v[82:83] op_sel_hi:[0,1,0]
	v_pk_fma_f32 v[80:81], v[58:59], v[80:81], v[82:83] op_sel_hi:[0,1,0]
	v_pk_fma_f32 v[98:99], v[58:59], v[74:75], v[82:83] op_sel_hi:[0,1,0]
	v_lshlrev_b32_e32 v74, 16, v77
	v_and_b32_e32 v75, 0xffff0000, v77
	v_pk_fma_f32 v[94:95], v[58:59], v[94:95], v[82:83] op_sel_hi:[0,1,0]
	v_pk_fma_f32 v[100:101], v[58:59], v[74:75], v[82:83] op_sel_hi:[0,1,0]
	v_cvt_pk_bf16_f32 v74, v90, v91
	v_cvt_pk_bf16_f32 v75, v78, v79
	v_cvt_pk_bf16_f32 v76, v92, v93
	v_cvt_pk_bf16_f32 v77, v80, v81
	global_store_dwordx4 v[102:103], v[74:77], off
	v_readlane_b32 s40, v245, 29
	v_readlane_b32 s41, v245, 30
	v_cvt_pk_bf16_f32 v74, v94, v95
	v_cvt_pk_bf16_f32 v75, v96, v97
	v_cvt_pk_bf16_f32 v76, v98, v99
	v_cvt_pk_bf16_f32 v77, v100, v101
	global_store_dwordx4 v[102:103], v[74:77], off offset:512
	v_readlane_b32 s42, v245, 31
	v_readlane_b32 s43, v245, 32
	s_waitcnt vmcnt(15)
	v_lshlrev_b32_e32 v74, 16, v62
	v_and_b32_e32 v75, 0xffff0000, v62
	v_lshlrev_b32_e32 v62, 16, v63
	v_and_b32_e32 v63, 0xffff0000, v63
	v_pk_mul_f32 v[62:63], v[58:59], v[62:63] op_sel:[1,0]
	v_lshlrev_b32_e32 v76, 16, v64
	v_pk_fma_f32 v[62:63], v[78:79], v[54:55], v[62:63] op_sel:[0,1,0]
	v_and_b32_e32 v77, 0xffff0000, v64
	v_lshlrev_b32_e32 v64, 16, v65
	v_and_b32_e32 v65, 0xffff0000, v65
	s_waitcnt vmcnt(14)
	v_lshlrev_b32_e32 v78, 16, v50
	v_and_b32_e32 v79, 0xffff0000, v50
	v_lshlrev_b32_e32 v50, 16, v51
	v_and_b32_e32 v51, 0xffff0000, v51
	v_pk_mul_f32 v[64:65], v[58:59], v[64:65] op_sel:[1,0]
	v_pk_mul_f32 v[50:51], v[58:59], v[50:51] op_sel:[1,0]
	v_pk_fma_f32 v[64:65], v[80:81], v[54:55], v[64:65] op_sel:[0,1,0]
	v_pk_fma_f32 v[80:81], v[96:97], v[54:55], v[50:51] op_sel:[0,1,0]
	v_lshlrev_b32_e32 v50, 16, v52
	v_and_b32_e32 v51, 0xffff0000, v52
	v_pk_mul_f32 v[74:75], v[58:59], v[74:75] op_sel:[1,0]
	v_pk_mul_f32 v[50:51], v[58:59], v[50:51] op_sel:[1,0]
	v_pk_fma_f32 v[74:75], v[90:91], v[54:55], v[74:75] op_sel:[0,1,0]
	v_pk_mul_f32 v[76:77], v[58:59], v[76:77] op_sel:[1,0]
	v_pk_fma_f32 v[90:91], v[98:99], v[54:55], v[50:51] op_sel:[0,1,0]
	v_lshlrev_b32_e32 v50, 16, v53
	v_and_b32_e32 v51, 0xffff0000, v53
	v_pk_fma_f32 v[76:77], v[92:93], v[54:55], v[76:77] op_sel:[0,1,0]
	v_pk_mul_f32 v[78:79], v[58:59], v[78:79] op_sel:[1,0]
	v_pk_mul_f32 v[50:51], v[58:59], v[50:51] op_sel:[1,0]
	v_add_co_u32_e32 v58, vcc, s7, v86
	v_pk_fma_f32 v[78:79], v[94:95], v[54:55], v[78:79] op_sel:[0,1,0]
	v_pk_fma_f32 v[54:55], v[100:101], v[54:55], v[50:51] op_sel:[0,1,0]
	v_cvt_pk_bf16_f32 v50, v74, v75
	v_cvt_pk_bf16_f32 v51, v62, v63
	v_cvt_pk_bf16_f32 v52, v76, v77
	v_cvt_pk_bf16_f32 v53, v64, v65
	v_addc_co_u32_e32 v59, vcc, 0, v87, vcc
	global_store_dwordx4 v[58:59], v[50:53], off
	s_mov_b32 s7, 0x27be0000
	v_readlane_b32 s44, v245, 33
	v_cvt_pk_bf16_f32 v50, v78, v79
	v_cvt_pk_bf16_f32 v51, v80, v81
	v_cvt_pk_bf16_f32 v52, v90, v91
	v_cvt_pk_bf16_f32 v53, v54, v55
	global_store_dwordx4 v[58:59], v[50:53], off offset:512
	s_waitcnt vmcnt(14)
	v_lshlrev_b32_e32 v58, 16, v42
	v_and_b32_e32 v59, 0xffff0000, v42
	v_lshlrev_b32_e32 v50, 16, v46
	v_and_b32_e32 v51, 0xffff0000, v46
	v_lshlrev_b32_e32 v46, 16, v47
	v_and_b32_e32 v47, 0xffff0000, v47
	v_lshlrev_b32_e32 v42, 16, v43
	v_and_b32_e32 v43, 0xffff0000, v43
	v_pk_mul_f32 v[46:47], v[60:61], v[46:47] op_sel_hi:[0,1]
	v_pk_mul_f32 v[42:43], v[60:61], v[42:43] op_sel_hi:[0,1]
	v_pk_fma_f32 v[46:47], v[62:63], v[56:57], v[46:47] op_sel_hi:[1,0,1]
	v_lshlrev_b32_e32 v52, 16, v48
	v_and_b32_e32 v53, 0xffff0000, v48
	v_lshlrev_b32_e32 v48, 16, v49
	v_and_b32_e32 v49, 0xffff0000, v49
	v_pk_fma_f32 v[62:63], v[80:81], v[56:57], v[42:43] op_sel_hi:[1,0,1]
	v_lshlrev_b32_e32 v42, 16, v44
	v_and_b32_e32 v43, 0xffff0000, v44
	v_pk_mul_f32 v[48:49], v[60:61], v[48:49] op_sel_hi:[0,1]
	v_pk_mul_f32 v[42:43], v[60:61], v[42:43] op_sel_hi:[0,1]
	v_pk_mul_f32 v[50:51], v[60:61], v[50:51] op_sel_hi:[0,1]
	v_pk_mul_f32 v[52:53], v[60:61], v[52:53] op_sel_hi:[0,1]
	v_pk_fma_f32 v[48:49], v[64:65], v[56:57], v[48:49] op_sel_hi:[1,0,1]
	v_pk_fma_f32 v[64:65], v[90:91], v[56:57], v[42:43] op_sel_hi:[1,0,1]
	v_lshlrev_b32_e32 v42, 16, v45
	v_and_b32_e32 v43, 0xffff0000, v45
	v_pk_fma_f32 v[50:51], v[74:75], v[56:57], v[50:51] op_sel_hi:[1,0,1]
	v_pk_fma_f32 v[52:53], v[76:77], v[56:57], v[52:53] op_sel_hi:[1,0,1]
	v_pk_mul_f32 v[58:59], v[60:61], v[58:59] op_sel_hi:[0,1]
	v_pk_mul_f32 v[42:43], v[60:61], v[42:43] op_sel_hi:[0,1]
	v_add_co_u32_e32 v74, vcc, s7, v86
	v_pk_fma_f32 v[58:59], v[78:79], v[56:57], v[58:59] op_sel_hi:[1,0,1]
	v_pk_fma_f32 v[54:55], v[54:55], v[56:57], v[42:43] op_sel_hi:[1,0,1]
	v_cvt_pk_bf16_f32 v42, v50, v51
	v_cvt_pk_bf16_f32 v43, v46, v47
	v_cvt_pk_bf16_f32 v44, v52, v53
	v_cvt_pk_bf16_f32 v45, v48, v49
	v_addc_co_u32_e32 v75, vcc, 0, v87, vcc
	global_store_dwordx4 v[74:75], v[42:45], off
	s_mov_b32 s7, 0x27c00000
	v_readlane_b32 s45, v245, 34
	v_cvt_pk_bf16_f32 v42, v58, v59
	v_cvt_pk_bf16_f32 v43, v62, v63
	v_cvt_pk_bf16_f32 v44, v64, v65
	v_cvt_pk_bf16_f32 v45, v54, v55
	global_store_dwordx4 v[74:75], v[42:45], off offset:512
	v_readlane_b32 s46, v245, 35
	v_readlane_b32 s47, v245, 36
	s_waitcnt vmcnt(15)
	v_lshlrev_b32_e32 v44, 16, v38
	v_and_b32_e32 v45, 0xffff0000, v38
	v_mov_b32_e32 v38, v61
	v_mov_b32_e32 v42, v57
	v_pk_mul_f32 v[44:45], v[38:39], v[44:45] op_sel_hi:[0,1]
	v_pk_fma_f32 v[44:45], v[50:51], v[42:43], v[44:45] op_sel_hi:[1,0,1]
	v_lshlrev_b32_e32 v50, 16, v39
	v_and_b32_e32 v51, 0xffff0000, v39
	v_pk_mul_f32 v[50:51], v[38:39], v[50:51] op_sel_hi:[0,1]
	v_pk_fma_f32 v[46:47], v[46:47], v[42:43], v[50:51] op_sel_hi:[1,0,1]
	v_lshlrev_b32_e32 v50, 16, v40
	v_and_b32_e32 v51, 0xffff0000, v40
	v_lshlrev_b32_e32 v40, 16, v41
	v_and_b32_e32 v41, 0xffff0000, v41
	v_pk_mul_f32 v[40:41], v[38:39], v[40:41] op_sel_hi:[0,1]
	v_pk_fma_f32 v[40:41], v[48:49], v[42:43], v[40:41] op_sel_hi:[1,0,1]
	s_waitcnt vmcnt(14)
	v_lshlrev_b32_e32 v48, 16, v34
	v_and_b32_e32 v49, 0xffff0000, v34
	v_lshlrev_b32_e32 v34, 16, v35
	v_and_b32_e32 v35, 0xffff0000, v35
	v_pk_mul_f32 v[50:51], v[38:39], v[50:51] op_sel_hi:[0,1]
	v_pk_mul_f32 v[34:35], v[38:39], v[34:35] op_sel_hi:[0,1]
	v_pk_fma_f32 v[50:51], v[52:53], v[42:43], v[50:51] op_sel_hi:[1,0,1]
	v_pk_fma_f32 v[52:53], v[62:63], v[42:43], v[34:35] op_sel_hi:[1,0,1]
	v_lshlrev_b32_e32 v34, 16, v36
	v_and_b32_e32 v35, 0xffff0000, v36
	v_pk_mul_f32 v[34:35], v[38:39], v[34:35] op_sel_hi:[0,1]
	v_pk_fma_f32 v[56:57], v[64:65], v[42:43], v[34:35] op_sel_hi:[1,0,1]
	v_lshlrev_b32_e32 v34, 16, v37
	v_and_b32_e32 v35, 0xffff0000, v37
	v_pk_mul_f32 v[48:49], v[38:39], v[48:49] op_sel_hi:[0,1]
	v_pk_mul_f32 v[34:35], v[38:39], v[34:35] op_sel_hi:[0,1]
	v_pk_fma_f32 v[48:49], v[58:59], v[42:43], v[48:49] op_sel_hi:[1,0,1]
	v_pk_fma_f32 v[38:39], v[54:55], v[42:43], v[34:35] op_sel_hi:[1,0,1]
	v_add_co_u32_e32 v42, vcc, s7, v86
	v_cvt_pk_bf16_f32 v34, v44, v45
	v_cvt_pk_bf16_f32 v35, v46, v47
	v_cvt_pk_bf16_f32 v36, v50, v51
	v_cvt_pk_bf16_f32 v37, v40, v41
	v_addc_co_u32_e32 v43, vcc, 0, v87, vcc
	global_store_dwordx4 v[42:43], v[34:37], off
	s_mov_b32 s7, 0x27c20000
	v_readlane_b32 s48, v245, 37
	v_cvt_pk_bf16_f32 v34, v48, v49
	v_cvt_pk_bf16_f32 v35, v52, v53
	v_cvt_pk_bf16_f32 v36, v56, v57
	v_cvt_pk_bf16_f32 v37, v38, v39
	global_store_dwordx4 v[42:43], v[34:37], off offset:512
	v_readlane_b32 s49, v245, 38
	s_waitcnt vmcnt(15)
	v_lshlrev_b32_e32 v36, 16, v32
	v_and_b32_e32 v37, 0xffff0000, v32
	v_lshlrev_b32_e32 v32, 16, v33
	v_and_b32_e32 v33, 0xffff0000, v33
	s_waitcnt lgkmcnt(0)
	v_pk_mul_f32 v[32:33], v[70:71], v[32:33] op_sel_hi:[0,1]
	v_pk_fma_f32 v[32:33], v[40:41], v[66:67], v[32:33] op_sel_hi:[1,0,1]
	s_waitcnt vmcnt(14)
	v_lshlrev_b32_e32 v40, 16, v26
	v_and_b32_e32 v41, 0xffff0000, v26
	v_lshlrev_b32_e32 v26, 16, v27
	v_and_b32_e32 v27, 0xffff0000, v27
	v_pk_mul_f32 v[26:27], v[70:71], v[26:27] op_sel_hi:[0,1]
	v_lshlrev_b32_e32 v34, 16, v30
	v_and_b32_e32 v35, 0xffff0000, v30
	v_pk_fma_f32 v[42:43], v[52:53], v[66:67], v[26:27] op_sel_hi:[1,0,1]
	v_lshlrev_b32_e32 v26, 16, v28
	v_and_b32_e32 v27, 0xffff0000, v28
	v_pk_mul_f32 v[34:35], v[70:71], v[34:35] op_sel_hi:[0,1]
	v_lshlrev_b32_e32 v30, 16, v31
	v_and_b32_e32 v31, 0xffff0000, v31
	v_pk_mul_f32 v[26:27], v[70:71], v[26:27] op_sel_hi:[0,1]
	v_pk_fma_f32 v[34:35], v[44:45], v[66:67], v[34:35] op_sel_hi:[1,0,1]
	v_pk_mul_f32 v[30:31], v[70:71], v[30:31] op_sel_hi:[0,1]
	v_pk_mul_f32 v[36:37], v[70:71], v[36:37] op_sel_hi:[0,1]
	v_pk_fma_f32 v[44:45], v[56:57], v[66:67], v[26:27] op_sel_hi:[1,0,1]
	v_lshlrev_b32_e32 v26, 16, v29
	v_and_b32_e32 v27, 0xffff0000, v29
	v_pk_fma_f32 v[30:31], v[46:47], v[66:67], v[30:31] op_sel_hi:[1,0,1]
	v_pk_fma_f32 v[36:37], v[50:51], v[66:67], v[36:37] op_sel_hi:[1,0,1]
	v_pk_mul_f32 v[40:41], v[70:71], v[40:41] op_sel_hi:[0,1]
	v_pk_mul_f32 v[26:27], v[70:71], v[26:27] op_sel_hi:[0,1]
	v_add_co_u32_e32 v46, vcc, s7, v86
	v_pk_fma_f32 v[40:41], v[48:49], v[66:67], v[40:41] op_sel_hi:[1,0,1]
	v_pk_fma_f32 v[38:39], v[38:39], v[66:67], v[26:27] op_sel_hi:[1,0,1]
	v_cvt_pk_bf16_f32 v26, v34, v35
	v_cvt_pk_bf16_f32 v27, v30, v31
	v_cvt_pk_bf16_f32 v28, v36, v37
	v_cvt_pk_bf16_f32 v29, v32, v33
	v_addc_co_u32_e32 v47, vcc, 0, v87, vcc
	global_store_dwordx4 v[46:47], v[26:29], off
	s_mov_b32 s7, 0x27c40000
	s_nop 0
	v_cvt_pk_bf16_f32 v26, v40, v41
	v_cvt_pk_bf16_f32 v27, v42, v43
	v_cvt_pk_bf16_f32 v28, v44, v45
	v_cvt_pk_bf16_f32 v29, v38, v39
	global_store_dwordx4 v[46:47], v[26:29], off offset:512
	s_waitcnt vmcnt(15)
	s_nop 0
	v_lshlrev_b32_e32 v26, 16, v22
	v_and_b32_e32 v27, 0xffff0000, v22
	v_lshlrev_b32_e32 v22, 16, v23
	v_and_b32_e32 v23, 0xffff0000, v23
	v_pk_mul_f32 v[22:23], v[70:71], v[22:23] op_sel:[1,0]
	v_lshlrev_b32_e32 v28, 16, v24
	v_pk_fma_f32 v[22:23], v[30:31], v[66:67], v[22:23] op_sel:[0,1,0]
	v_and_b32_e32 v29, 0xffff0000, v24
	v_lshlrev_b32_e32 v24, 16, v25
	v_and_b32_e32 v25, 0xffff0000, v25
	s_waitcnt vmcnt(14)
	v_lshlrev_b32_e32 v30, 16, v18
	v_and_b32_e32 v31, 0xffff0000, v18
	v_lshlrev_b32_e32 v18, 16, v19
	v_and_b32_e32 v19, 0xffff0000, v19
	v_pk_mul_f32 v[24:25], v[70:71], v[24:25] op_sel:[1,0]
	v_pk_mul_f32 v[18:19], v[70:71], v[18:19] op_sel:[1,0]
	v_pk_fma_f32 v[24:25], v[32:33], v[66:67], v[24:25] op_sel:[0,1,0]
	v_pk_fma_f32 v[32:33], v[42:43], v[66:67], v[18:19] op_sel:[0,1,0]
	v_lshlrev_b32_e32 v18, 16, v20
	v_and_b32_e32 v19, 0xffff0000, v20
	v_pk_mul_f32 v[26:27], v[70:71], v[26:27] op_sel:[1,0]
	v_pk_mul_f32 v[18:19], v[70:71], v[18:19] op_sel:[1,0]
	v_pk_fma_f32 v[26:27], v[34:35], v[66:67], v[26:27] op_sel:[0,1,0]
	v_pk_fma_f32 v[34:35], v[44:45], v[66:67], v[18:19] op_sel:[0,1,0]
	v_lshlrev_b32_e32 v18, 16, v21
	v_and_b32_e32 v19, 0xffff0000, v21
	v_pk_mul_f32 v[28:29], v[70:71], v[28:29] op_sel:[1,0]
	v_pk_mul_f32 v[18:19], v[70:71], v[18:19] op_sel:[1,0]
	v_pk_fma_f32 v[28:29], v[36:37], v[66:67], v[28:29] op_sel:[0,1,0]
	v_pk_mul_f32 v[30:31], v[70:71], v[30:31] op_sel:[1,0]
	v_pk_fma_f32 v[36:37], v[38:39], v[66:67], v[18:19] op_sel:[0,1,0]
	v_add_co_u32_e32 v38, vcc, s7, v86
	v_pk_fma_f32 v[30:31], v[40:41], v[66:67], v[30:31] op_sel:[0,1,0]
	v_cvt_pk_bf16_f32 v18, v26, v27
	v_cvt_pk_bf16_f32 v19, v22, v23
	v_cvt_pk_bf16_f32 v20, v28, v29
	v_cvt_pk_bf16_f32 v21, v24, v25
	v_addc_co_u32_e32 v39, vcc, 0, v87, vcc
	global_store_dwordx4 v[38:39], v[18:21], off
	s_mov_b32 s7, 0x27c60000
	s_nop 0
	v_cvt_pk_bf16_f32 v18, v30, v31
	v_cvt_pk_bf16_f32 v19, v32, v33
	v_cvt_pk_bf16_f32 v20, v34, v35
	v_cvt_pk_bf16_f32 v21, v36, v37
	global_store_dwordx4 v[38:39], v[18:21], off offset:512
	s_waitcnt vmcnt(15)
	s_nop 0
	v_lshlrev_b32_e32 v18, 16, v14
	v_and_b32_e32 v19, 0xffff0000, v14
	v_lshlrev_b32_e32 v14, 16, v15
	v_and_b32_e32 v15, 0xffff0000, v15
	v_pk_mul_f32 v[14:15], v[72:73], v[14:15] op_sel_hi:[0,1]
	v_pk_fma_f32 v[14:15], v[22:23], v[68:69], v[14:15] op_sel_hi:[1,0,1]
	v_lshlrev_b32_e32 v20, 16, v16
	v_and_b32_e32 v21, 0xffff0000, v16
	v_lshlrev_b32_e32 v16, 16, v17
	v_and_b32_e32 v17, 0xffff0000, v17
	s_waitcnt vmcnt(14)
	v_lshlrev_b32_e32 v22, 16, v10
	v_and_b32_e32 v23, 0xffff0000, v10
	v_lshlrev_b32_e32 v10, 16, v11
	v_and_b32_e32 v11, 0xffff0000, v11
	v_pk_mul_f32 v[16:17], v[72:73], v[16:17] op_sel_hi:[0,1]
	v_pk_mul_f32 v[10:11], v[72:73], v[10:11] op_sel_hi:[0,1]
	v_pk_fma_f32 v[16:17], v[24:25], v[68:69], v[16:17] op_sel_hi:[1,0,1]
	v_pk_fma_f32 v[24:25], v[32:33], v[68:69], v[10:11] op_sel_hi:[1,0,1]
	v_lshlrev_b32_e32 v10, 16, v12
	v_and_b32_e32 v11, 0xffff0000, v12
	v_pk_mul_f32 v[18:19], v[72:73], v[18:19] op_sel_hi:[0,1]
	v_pk_mul_f32 v[10:11], v[72:73], v[10:11] op_sel_hi:[0,1]
	v_pk_fma_f32 v[18:19], v[26:27], v[68:69], v[18:19] op_sel_hi:[1,0,1]
	v_pk_mul_f32 v[20:21], v[72:73], v[20:21] op_sel_hi:[0,1]
	v_pk_mul_f32 v[22:23], v[72:73], v[22:23] op_sel_hi:[0,1]
	v_pk_fma_f32 v[26:27], v[34:35], v[68:69], v[10:11] op_sel_hi:[1,0,1]
	v_lshlrev_b32_e32 v10, 16, v13
	v_and_b32_e32 v11, 0xffff0000, v13
	v_pk_fma_f32 v[20:21], v[28:29], v[68:69], v[20:21] op_sel_hi:[1,0,1]
	v_pk_fma_f32 v[22:23], v[30:31], v[68:69], v[22:23] op_sel_hi:[1,0,1]
	v_pk_mul_f32 v[10:11], v[72:73], v[10:11] op_sel_hi:[0,1]
	v_add_co_u32_e32 v30, vcc, s7, v86
	v_pk_fma_f32 v[28:29], v[36:37], v[68:69], v[10:11] op_sel_hi:[1,0,1]
	v_cvt_pk_bf16_f32 v10, v18, v19
	v_cvt_pk_bf16_f32 v11, v14, v15
	v_cvt_pk_bf16_f32 v12, v20, v21
	v_cvt_pk_bf16_f32 v13, v16, v17
	v_addc_co_u32_e32 v31, vcc, 0, v87, vcc
	global_store_dwordx4 v[30:31], v[10:13], off
	s_mov_b32 s7, 0x27c80000
	s_nop 0
	v_cvt_pk_bf16_f32 v10, v22, v23
	v_cvt_pk_bf16_f32 v11, v24, v25
	v_cvt_pk_bf16_f32 v12, v26, v27
	v_cvt_pk_bf16_f32 v13, v28, v29
	global_store_dwordx4 v[30:31], v[10:13], off offset:512
	s_waitcnt vmcnt(15)
	s_nop 0
	v_lshlrev_b32_e32 v12, 16, v6
	v_and_b32_e32 v13, 0xffff0000, v6
	v_mov_b32_e32 v6, v73
	v_mov_b32_e32 v10, v69
	v_pk_mul_f32 v[12:13], v[6:7], v[12:13] op_sel_hi:[0,1]
	v_pk_fma_f32 v[90:91], v[18:19], v[10:11], v[12:13] op_sel_hi:[1,0,1]
	v_lshlrev_b32_e32 v12, 16, v7
	v_and_b32_e32 v13, 0xffff0000, v7
	v_pk_mul_f32 v[12:13], v[6:7], v[12:13] op_sel_hi:[0,1]
	v_pk_fma_f32 v[92:93], v[14:15], v[10:11], v[12:13] op_sel_hi:[1,0,1]
	v_lshlrev_b32_e32 v12, 16, v8
	v_and_b32_e32 v13, 0xffff0000, v8
	v_lshlrev_b32_e32 v8, 16, v9
	v_and_b32_e32 v9, 0xffff0000, v9
	v_pk_mul_f32 v[8:9], v[6:7], v[8:9] op_sel_hi:[0,1]
	v_pk_fma_f32 v[96:97], v[16:17], v[10:11], v[8:9] op_sel_hi:[1,0,1]
	s_waitcnt vmcnt(14)
	v_lshlrev_b32_e32 v8, 16, v2
	v_and_b32_e32 v9, 0xffff0000, v2
	v_lshlrev_b32_e32 v2, 16, v3
	v_and_b32_e32 v3, 0xffff0000, v3
	v_pk_mul_f32 v[2:3], v[6:7], v[2:3] op_sel_hi:[0,1]
	v_pk_fma_f32 v[100:101], v[24:25], v[10:11], v[2:3] op_sel_hi:[1,0,1]
	v_lshlrev_b32_e32 v2, 16, v4
	v_and_b32_e32 v3, 0xffff0000, v4
	v_pk_mul_f32 v[2:3], v[6:7], v[2:3] op_sel_hi:[0,1]
	v_pk_mul_f32 v[12:13], v[6:7], v[12:13] op_sel_hi:[0,1]
	v_pk_fma_f32 v[102:103], v[26:27], v[10:11], v[2:3] op_sel_hi:[1,0,1]
	v_lshlrev_b32_e32 v2, 16, v5
	v_and_b32_e32 v3, 0xffff0000, v5
	v_pk_fma_f32 v[94:95], v[20:21], v[10:11], v[12:13] op_sel_hi:[1,0,1]
	v_pk_mul_f32 v[8:9], v[6:7], v[8:9] op_sel_hi:[0,1]
	v_pk_mul_f32 v[2:3], v[6:7], v[2:3] op_sel_hi:[0,1]
	v_add_co_u32_e32 v6, vcc, s7, v86
	v_pk_fma_f32 v[98:99], v[22:23], v[10:11], v[8:9] op_sel_hi:[1,0,1]
	v_pk_fma_f32 v[104:105], v[28:29], v[10:11], v[2:3] op_sel_hi:[1,0,1]
	v_cvt_pk_bf16_f32 v2, v90, v91
	v_cvt_pk_bf16_f32 v3, v92, v93
	v_cvt_pk_bf16_f32 v4, v94, v95
	v_cvt_pk_bf16_f32 v5, v96, v97
	v_addc_co_u32_e32 v7, vcc, 0, v87, vcc
	global_store_dwordx4 v[6:7], v[2:5], off
	s_mov_b32 s7, 0x23c80000
	s_nop 0
	v_cvt_pk_bf16_f32 v2, v98, v99
	v_cvt_pk_bf16_f32 v3, v100, v101
	v_cvt_pk_bf16_f32 v4, v102, v103
	v_cvt_pk_bf16_f32 v5, v104, v105
	global_store_dwordx4 v[6:7], v[2:5], off offset:512
	s_nop 1
	v_add_co_u32_e32 v2, vcc, s7, v88
	s_mov_b32 s7, 0
	s_nop 0
	v_addc_co_u32_e32 v3, vcc, 0, v89, vcc
	s_waitcnt vmcnt(16)
	v_mov_b32_e32 v78, v110
	v_mov_b32_e32 v79, v111
	v_mov_b32_e32 v80, v112
	v_mov_b32_e32 v81, v113
	v_lshl_add_u64 v[2:3], v[88:89], 0, s[8:9]
	v_mov_b32_e32 v74, v114
	v_mov_b32_e32 v75, v115
	v_mov_b32_e32 v76, v116
	v_mov_b32_e32 v77, v117
	s_mov_b64 s[8:9], 0x23ca0000
	v_lshl_add_u64 v[2:3], v[88:89], 0, s[8:9]
	s_mov_b32 s8, 0x23ca0000
	v_add_co_u32_e32 v4, vcc, s8, v88
	s_mov_b64 s[8:9], 0x23cc0000
	s_nop 0
	v_addc_co_u32_e32 v5, vcc, 0, v89, vcc
	v_mov_b32_e32 v70, v118
	v_mov_b32_e32 v71, v119
	v_mov_b32_e32 v72, v120
	v_mov_b32_e32 v73, v121
	v_mov_b32_e32 v58, v122
	v_mov_b32_e32 v59, v123
	v_mov_b32_e32 v60, v124
	v_mov_b32_e32 v61, v125
	v_lshl_add_u64 v[2:3], v[88:89], 0, s[8:9]
	s_mov_b32 s8, 0x23cc0000
	v_add_co_u32_e32 v4, vcc, s8, v88
	s_mov_b64 s[8:9], 0x23ce0000
	s_nop 0
	v_addc_co_u32_e32 v5, vcc, 0, v89, vcc
	v_mov_b32_e32 v54, v126
	v_mov_b32_e32 v55, v127
	v_mov_b32_e32 v56, v128
	v_mov_b32_e32 v57, v129
	v_mov_b32_e32 v42, v130
	v_mov_b32_e32 v43, v131
	v_mov_b32_e32 v44, v132
	v_mov_b32_e32 v45, v133
	v_lshl_add_u64 v[2:3], v[88:89], 0, s[8:9]
	s_mov_b32 s8, 0x23ce0000
	v_add_co_u32_e32 v4, vcc, s8, v88
	s_mov_b64 s[8:9], 0x23d00000
	s_nop 0
	v_addc_co_u32_e32 v5, vcc, 0, v89, vcc
	v_mov_b32_e32 v38, v134
	v_mov_b32_e32 v39, v135
	v_mov_b32_e32 v40, v136
	v_mov_b32_e32 v41, v137
	v_mov_b32_e32 v34, v138
	v_mov_b32_e32 v35, v139
	v_mov_b32_e32 v36, v140
	v_mov_b32_e32 v37, v141
	v_lshl_add_u64 v[2:3], v[88:89], 0, s[8:9]
	s_mov_b32 s8, 0x23d00000
	v_add_co_u32_e32 v4, vcc, s8, v88
	s_mov_b64 s[8:9], 0x23d20000
	s_nop 0
	v_addc_co_u32_e32 v5, vcc, 0, v89, vcc
	v_mov_b32_e32 v30, v142
	v_mov_b32_e32 v31, v143
	v_mov_b32_e32 v32, v144
	v_mov_b32_e32 v33, v145
	v_mov_b32_e32 v26, v146
	v_mov_b32_e32 v27, v147
	v_mov_b32_e32 v28, v148
	v_mov_b32_e32 v29, v149
	v_lshl_add_u64 v[2:3], v[88:89], 0, s[8:9]
	s_mov_b32 s8, 0x23d20000
	v_add_co_u32_e32 v4, vcc, s8, v88
	s_mov_b64 s[8:9], 0x23d40000
	s_nop 0
	v_addc_co_u32_e32 v5, vcc, 0, v89, vcc
	v_mov_b32_e32 v22, v150
	v_mov_b32_e32 v23, v151
	v_mov_b32_e32 v24, v152
	v_mov_b32_e32 v25, v153
	v_mov_b32_e32 v18, v154
	v_mov_b32_e32 v19, v155
	v_mov_b32_e32 v20, v156
	v_mov_b32_e32 v21, v157
	v_lshl_add_u64 v[2:3], v[88:89], 0, s[8:9]
	s_mov_b32 s8, 0x23d40000
	v_add_co_u32_e32 v4, vcc, s8, v88
	s_mov_b64 s[8:9], 0x23d60000
	s_nop 0
	v_addc_co_u32_e32 v5, vcc, 0, v89, vcc
	v_mov_b32_e32 v14, v158
	v_mov_b32_e32 v15, v159
	v_mov_b32_e32 v16, v160
	v_mov_b32_e32 v17, v161
	v_mov_b32_e32 v10, v162
	v_mov_b32_e32 v11, v163
	v_mov_b32_e32 v12, v164
	v_mov_b32_e32 v13, v165
	v_lshl_add_u64 v[46:47], v[88:89], 0, s[8:9]
	s_mov_b32 s8, 0x23d60000
	v_add_co_u32_e32 v48, vcc, s8, v88
	s_mov_b32 s8, 0x27ca0000
	s_nop 0
	v_addc_co_u32_e32 v49, vcc, 0, v89, vcc
	v_mov_b32_e32 v6, v166
	v_mov_b32_e32 v7, v167
	v_mov_b32_e32 v8, v168
	v_mov_b32_e32 v9, v169
	v_mov_b32_e32 v2, v170
	v_mov_b32_e32 v3, v171
	v_mov_b32_e32 v4, v172
	v_mov_b32_e32 v5, v173
	ds_read_b128 v[62:65], v83 offset:96
	ds_read_b128 v[66:69], v83 offset:32
	ds_read_b128 v[50:53], v83 offset:112
	s_waitcnt vmcnt(15)
	v_lshlrev_b32_e32 v46, 16, v78
	v_and_b32_e32 v47, 0xffff0000, v78
	v_lshlrev_b32_e32 v78, 16, v79
	v_and_b32_e32 v79, 0xffff0000, v79
	s_waitcnt lgkmcnt(2)
	v_pk_mul_f32 v[88:89], v[62:63], v[46:47] op_sel_hi:[0,1]
	v_pk_mul_f32 v[78:79], v[62:63], v[78:79] op_sel_hi:[0,1]
	s_waitcnt lgkmcnt(1)
	v_pk_fma_f32 v[88:89], v[90:91], v[66:67], v[88:89] op_sel_hi:[1,0,1]
	v_pk_fma_f32 v[78:79], v[92:93], v[66:67], v[78:79] op_sel_hi:[1,0,1]
	v_lshlrev_b32_e32 v90, 16, v80
	v_and_b32_e32 v91, 0xffff0000, v80
	s_waitcnt vmcnt(14)
	v_lshlrev_b32_e32 v92, 16, v74
	v_and_b32_e32 v93, 0xffff0000, v74
	v_lshlrev_b32_e32 v74, 16, v75
	v_and_b32_e32 v75, 0xffff0000, v75
	v_pk_mul_f32 v[90:91], v[62:63], v[90:91] op_sel_hi:[0,1]
	v_pk_mul_f32 v[74:75], v[62:63], v[74:75] op_sel_hi:[0,1]
	v_pk_fma_f32 v[90:91], v[94:95], v[66:67], v[90:91] op_sel_hi:[1,0,1]
	v_lshlrev_b32_e32 v80, 16, v81
	v_and_b32_e32 v81, 0xffff0000, v81
	v_pk_fma_f32 v[94:95], v[100:101], v[66:67], v[74:75] op_sel_hi:[1,0,1]
	v_lshlrev_b32_e32 v74, 16, v76
	v_and_b32_e32 v75, 0xffff0000, v76
	v_pk_mul_f32 v[80:81], v[62:63], v[80:81] op_sel_hi:[0,1]
	v_pk_mul_f32 v[74:75], v[62:63], v[74:75] op_sel_hi:[0,1]
	v_pk_fma_f32 v[80:81], v[96:97], v[66:67], v[80:81] op_sel_hi:[1,0,1]
	v_pk_fma_f32 v[96:97], v[102:103], v[66:67], v[74:75] op_sel_hi:[1,0,1]
	v_lshlrev_b32_e32 v74, 16, v77
	v_and_b32_e32 v75, 0xffff0000, v77
	v_pk_mul_f32 v[92:93], v[62:63], v[92:93] op_sel_hi:[0,1]
	v_pk_mul_f32 v[74:75], v[62:63], v[74:75] op_sel_hi:[0,1]
	v_add_co_u32_e32 v100, vcc, s8, v86
	v_pk_fma_f32 v[92:93], v[98:99], v[66:67], v[92:93] op_sel_hi:[1,0,1]
	v_pk_fma_f32 v[98:99], v[104:105], v[66:67], v[74:75] op_sel_hi:[1,0,1]
	v_cvt_pk_bf16_f32 v74, v88, v89
	v_cvt_pk_bf16_f32 v75, v78, v79
	v_cvt_pk_bf16_f32 v76, v90, v91
	v_cvt_pk_bf16_f32 v77, v80, v81
	v_addc_co_u32_e32 v101, vcc, 0, v87, vcc
	global_store_dwordx4 v[100:101], v[74:77], off
	s_mov_b32 s8, 0x27cc0000
	ds_read_b128 v[46:49], v83 offset:48
	v_cvt_pk_bf16_f32 v74, v92, v93
	v_cvt_pk_bf16_f32 v75, v94, v95
	v_cvt_pk_bf16_f32 v76, v96, v97
	v_cvt_pk_bf16_f32 v77, v98, v99
	global_store_dwordx4 v[100:101], v[74:77], off offset:512
	s_waitcnt vmcnt(15)
	s_nop 0
	v_lshlrev_b32_e32 v74, 16, v70
	v_and_b32_e32 v75, 0xffff0000, v70
	v_lshlrev_b32_e32 v70, 16, v71
	v_and_b32_e32 v71, 0xffff0000, v71
	v_pk_mul_f32 v[70:71], v[62:63], v[70:71] op_sel:[1,0]
	v_lshlrev_b32_e32 v76, 16, v72
	v_pk_fma_f32 v[70:71], v[78:79], v[66:67], v[70:71] op_sel:[0,1,0]
	v_and_b32_e32 v77, 0xffff0000, v72
	v_lshlrev_b32_e32 v72, 16, v73
	v_and_b32_e32 v73, 0xffff0000, v73
	s_waitcnt vmcnt(14)
	v_lshlrev_b32_e32 v78, 16, v58
	v_and_b32_e32 v79, 0xffff0000, v58
	v_lshlrev_b32_e32 v58, 16, v59
	v_and_b32_e32 v59, 0xffff0000, v59
	v_pk_mul_f32 v[72:73], v[62:63], v[72:73] op_sel:[1,0]
	v_pk_mul_f32 v[58:59], v[62:63], v[58:59] op_sel:[1,0]
	v_pk_fma_f32 v[72:73], v[80:81], v[66:67], v[72:73] op_sel:[0,1,0]
	v_pk_fma_f32 v[80:81], v[94:95], v[66:67], v[58:59] op_sel:[0,1,0]
	v_lshlrev_b32_e32 v58, 16, v60
	v_and_b32_e32 v59, 0xffff0000, v60
	v_pk_mul_f32 v[74:75], v[62:63], v[74:75] op_sel:[1,0]
	v_pk_mul_f32 v[58:59], v[62:63], v[58:59] op_sel:[1,0]
	v_pk_fma_f32 v[74:75], v[88:89], v[66:67], v[74:75] op_sel:[0,1,0]
	v_pk_fma_f32 v[88:89], v[96:97], v[66:67], v[58:59] op_sel:[0,1,0]
	v_lshlrev_b32_e32 v58, 16, v61
	v_and_b32_e32 v59, 0xffff0000, v61
	v_pk_mul_f32 v[76:77], v[62:63], v[76:77] op_sel:[1,0]
	v_pk_mul_f32 v[78:79], v[62:63], v[78:79] op_sel:[1,0]
	v_pk_mul_f32 v[58:59], v[62:63], v[58:59] op_sel:[1,0]
	v_pk_fma_f32 v[76:77], v[90:91], v[66:67], v[76:77] op_sel:[0,1,0]
	v_pk_fma_f32 v[78:79], v[92:93], v[66:67], v[78:79] op_sel:[0,1,0]
	v_pk_fma_f32 v[62:63], v[98:99], v[66:67], v[58:59] op_sel:[0,1,0]
	v_add_co_u32_e32 v66, vcc, s8, v86
	v_cvt_pk_bf16_f32 v58, v74, v75
	v_cvt_pk_bf16_f32 v59, v70, v71
	v_cvt_pk_bf16_f32 v60, v76, v77
	v_cvt_pk_bf16_f32 v61, v72, v73
	v_addc_co_u32_e32 v67, vcc, 0, v87, vcc
	global_store_dwordx4 v[66:67], v[58:61], off
	s_mov_b32 s8, 0x27ce0000
	s_nop 0
	v_cvt_pk_bf16_f32 v58, v78, v79
	v_cvt_pk_bf16_f32 v59, v80, v81
	v_cvt_pk_bf16_f32 v60, v88, v89
	v_cvt_pk_bf16_f32 v61, v62, v63
	global_store_dwordx4 v[66:67], v[58:61], off offset:512
	s_waitcnt vmcnt(14)
	v_lshlrev_b32_e32 v66, 16, v42
	v_and_b32_e32 v67, 0xffff0000, v42
	v_lshlrev_b32_e32 v58, 16, v54
	v_and_b32_e32 v59, 0xffff0000, v54
	v_lshlrev_b32_e32 v54, 16, v55
	v_and_b32_e32 v55, 0xffff0000, v55
	v_lshlrev_b32_e32 v42, 16, v43
	v_and_b32_e32 v43, 0xffff0000, v43
	v_pk_mul_f32 v[54:55], v[64:65], v[54:55] op_sel_hi:[0,1]
	v_pk_mul_f32 v[42:43], v[64:65], v[42:43] op_sel_hi:[0,1]
	v_pk_fma_f32 v[54:55], v[70:71], v[68:69], v[54:55] op_sel_hi:[1,0,1]
	v_lshlrev_b32_e32 v60, 16, v56
	v_and_b32_e32 v61, 0xffff0000, v56
	v_lshlrev_b32_e32 v56, 16, v57
	v_and_b32_e32 v57, 0xffff0000, v57
	v_pk_fma_f32 v[70:71], v[80:81], v[68:69], v[42:43] op_sel_hi:[1,0,1]
	v_lshlrev_b32_e32 v42, 16, v44
	v_and_b32_e32 v43, 0xffff0000, v44
	v_pk_mul_f32 v[56:57], v[64:65], v[56:57] op_sel_hi:[0,1]
	v_pk_mul_f32 v[42:43], v[64:65], v[42:43] op_sel_hi:[0,1]
	v_pk_mul_f32 v[58:59], v[64:65], v[58:59] op_sel_hi:[0,1]
	v_pk_mul_f32 v[60:61], v[64:65], v[60:61] op_sel_hi:[0,1]
	v_pk_fma_f32 v[56:57], v[72:73], v[68:69], v[56:57] op_sel_hi:[1,0,1]
	v_pk_fma_f32 v[72:73], v[88:89], v[68:69], v[42:43] op_sel_hi:[1,0,1]
	v_lshlrev_b32_e32 v42, 16, v45
	v_and_b32_e32 v43, 0xffff0000, v45
	v_pk_fma_f32 v[58:59], v[74:75], v[68:69], v[58:59] op_sel_hi:[1,0,1]
	v_pk_fma_f32 v[60:61], v[76:77], v[68:69], v[60:61] op_sel_hi:[1,0,1]
	v_pk_mul_f32 v[66:67], v[64:65], v[66:67] op_sel_hi:[0,1]
	v_pk_mul_f32 v[42:43], v[64:65], v[42:43] op_sel_hi:[0,1]
	v_add_co_u32_e32 v74, vcc, s8, v86
	v_pk_fma_f32 v[66:67], v[78:79], v[68:69], v[66:67] op_sel_hi:[1,0,1]
	v_pk_fma_f32 v[62:63], v[62:63], v[68:69], v[42:43] op_sel_hi:[1,0,1]
	v_cvt_pk_bf16_f32 v42, v58, v59
	v_cvt_pk_bf16_f32 v43, v54, v55
	v_cvt_pk_bf16_f32 v44, v60, v61
	v_cvt_pk_bf16_f32 v45, v56, v57
	v_addc_co_u32_e32 v75, vcc, 0, v87, vcc
	global_store_dwordx4 v[74:75], v[42:45], off
	s_mov_b32 s8, 0x27d00000
	s_nop 0
	v_cvt_pk_bf16_f32 v42, v66, v67
	v_cvt_pk_bf16_f32 v43, v70, v71
	v_cvt_pk_bf16_f32 v44, v72, v73
	v_cvt_pk_bf16_f32 v45, v62, v63
	global_store_dwordx4 v[74:75], v[42:45], off offset:512
	s_waitcnt vmcnt(15)
	s_nop 0
	v_lshlrev_b32_e32 v44, 16, v38
	v_and_b32_e32 v45, 0xffff0000, v38
	v_mov_b32_e32 v38, v65
	v_mov_b32_e32 v42, v69
	v_pk_mul_f32 v[44:45], v[38:39], v[44:45] op_sel_hi:[0,1]
	v_pk_fma_f32 v[44:45], v[58:59], v[42:43], v[44:45] op_sel_hi:[1,0,1]
	v_lshlrev_b32_e32 v58, 16, v39
	v_and_b32_e32 v59, 0xffff0000, v39
	v_pk_mul_f32 v[58:59], v[38:39], v[58:59] op_sel_hi:[0,1]
	v_pk_fma_f32 v[54:55], v[54:55], v[42:43], v[58:59] op_sel_hi:[1,0,1]
	v_lshlrev_b32_e32 v58, 16, v40
	v_and_b32_e32 v59, 0xffff0000, v40
	v_lshlrev_b32_e32 v40, 16, v41
	v_and_b32_e32 v41, 0xffff0000, v41
	v_pk_mul_f32 v[40:41], v[38:39], v[40:41] op_sel_hi:[0,1]
	v_pk_fma_f32 v[40:41], v[56:57], v[42:43], v[40:41] op_sel_hi:[1,0,1]
	s_waitcnt vmcnt(14)
	v_lshlrev_b32_e32 v56, 16, v34
	v_and_b32_e32 v57, 0xffff0000, v34
	v_lshlrev_b32_e32 v34, 16, v35
	v_and_b32_e32 v35, 0xffff0000, v35
	v_pk_mul_f32 v[58:59], v[38:39], v[58:59] op_sel_hi:[0,1]
	v_pk_mul_f32 v[34:35], v[38:39], v[34:35] op_sel_hi:[0,1]
	v_pk_fma_f32 v[58:59], v[60:61], v[42:43], v[58:59] op_sel_hi:[1,0,1]
	v_pk_fma_f32 v[60:61], v[70:71], v[42:43], v[34:35] op_sel_hi:[1,0,1]
	v_lshlrev_b32_e32 v34, 16, v36
	v_and_b32_e32 v35, 0xffff0000, v36
	v_pk_mul_f32 v[34:35], v[38:39], v[34:35] op_sel_hi:[0,1]
	v_pk_fma_f32 v[64:65], v[72:73], v[42:43], v[34:35] op_sel_hi:[1,0,1]
	v_lshlrev_b32_e32 v34, 16, v37
	v_and_b32_e32 v35, 0xffff0000, v37
	v_pk_mul_f32 v[56:57], v[38:39], v[56:57] op_sel_hi:[0,1]
	v_pk_mul_f32 v[34:35], v[38:39], v[34:35] op_sel_hi:[0,1]
	v_pk_fma_f32 v[56:57], v[66:67], v[42:43], v[56:57] op_sel_hi:[1,0,1]
	v_pk_fma_f32 v[38:39], v[62:63], v[42:43], v[34:35] op_sel_hi:[1,0,1]
	v_add_co_u32_e32 v42, vcc, s8, v86
	v_cvt_pk_bf16_f32 v34, v44, v45
	v_cvt_pk_bf16_f32 v35, v54, v55
	v_cvt_pk_bf16_f32 v36, v58, v59
	v_cvt_pk_bf16_f32 v37, v40, v41
	v_addc_co_u32_e32 v43, vcc, 0, v87, vcc
	global_store_dwordx4 v[42:43], v[34:37], off
	s_mov_b32 s8, 0x27d20000
	s_nop 0
	v_cvt_pk_bf16_f32 v34, v56, v57
	v_cvt_pk_bf16_f32 v35, v60, v61
	v_cvt_pk_bf16_f32 v36, v64, v65
	v_cvt_pk_bf16_f32 v37, v38, v39
	global_store_dwordx4 v[42:43], v[34:37], off offset:512
	s_waitcnt vmcnt(15)
	s_nop 0
	v_lshlrev_b32_e32 v36, 16, v32
	v_and_b32_e32 v37, 0xffff0000, v32
	v_lshlrev_b32_e32 v32, 16, v33
	v_and_b32_e32 v33, 0xffff0000, v33
	s_waitcnt lgkmcnt(1)
	v_pk_mul_f32 v[32:33], v[50:51], v[32:33] op_sel_hi:[0,1]
	s_waitcnt lgkmcnt(0)
	v_pk_fma_f32 v[32:33], v[40:41], v[46:47], v[32:33] op_sel_hi:[1,0,1]
	s_waitcnt vmcnt(14)
	v_lshlrev_b32_e32 v40, 16, v26
	v_and_b32_e32 v41, 0xffff0000, v26
	v_lshlrev_b32_e32 v26, 16, v27
	v_and_b32_e32 v27, 0xffff0000, v27
	v_pk_mul_f32 v[26:27], v[50:51], v[26:27] op_sel_hi:[0,1]
	v_lshlrev_b32_e32 v34, 16, v30
	v_and_b32_e32 v35, 0xffff0000, v30
	v_pk_fma_f32 v[42:43], v[60:61], v[46:47], v[26:27] op_sel_hi:[1,0,1]
	v_lshlrev_b32_e32 v26, 16, v28
	v_and_b32_e32 v27, 0xffff0000, v28
	v_pk_mul_f32 v[34:35], v[50:51], v[34:35] op_sel_hi:[0,1]
	v_lshlrev_b32_e32 v30, 16, v31
	v_and_b32_e32 v31, 0xffff0000, v31
	v_pk_mul_f32 v[26:27], v[50:51], v[26:27] op_sel_hi:[0,1]
	v_pk_fma_f32 v[34:35], v[44:45], v[46:47], v[34:35] op_sel_hi:[1,0,1]
	v_pk_mul_f32 v[30:31], v[50:51], v[30:31] op_sel_hi:[0,1]
	v_pk_mul_f32 v[36:37], v[50:51], v[36:37] op_sel_hi:[0,1]
	v_pk_fma_f32 v[44:45], v[64:65], v[46:47], v[26:27] op_sel_hi:[1,0,1]
	v_lshlrev_b32_e32 v26, 16, v29
	v_and_b32_e32 v27, 0xffff0000, v29
	v_pk_fma_f32 v[30:31], v[54:55], v[46:47], v[30:31] op_sel_hi:[1,0,1]
	v_pk_fma_f32 v[36:37], v[58:59], v[46:47], v[36:37] op_sel_hi:[1,0,1]
	v_pk_mul_f32 v[40:41], v[50:51], v[40:41] op_sel_hi:[0,1]
	v_pk_mul_f32 v[26:27], v[50:51], v[26:27] op_sel_hi:[0,1]
	v_add_co_u32_e32 v54, vcc, s8, v86
	v_pk_fma_f32 v[40:41], v[56:57], v[46:47], v[40:41] op_sel_hi:[1,0,1]
	v_pk_fma_f32 v[38:39], v[38:39], v[46:47], v[26:27] op_sel_hi:[1,0,1]
	v_cvt_pk_bf16_f32 v26, v34, v35
	v_cvt_pk_bf16_f32 v27, v30, v31
	v_cvt_pk_bf16_f32 v28, v36, v37
	v_cvt_pk_bf16_f32 v29, v32, v33
	v_addc_co_u32_e32 v55, vcc, 0, v87, vcc
	global_store_dwordx4 v[54:55], v[26:29], off
	s_mov_b32 s8, 0x27d40000
	s_nop 0
	v_cvt_pk_bf16_f32 v26, v40, v41
	v_cvt_pk_bf16_f32 v27, v42, v43
	v_cvt_pk_bf16_f32 v28, v44, v45
	v_cvt_pk_bf16_f32 v29, v38, v39
	global_store_dwordx4 v[54:55], v[26:29], off offset:512
	s_waitcnt vmcnt(15)
	s_nop 0
	v_lshlrev_b32_e32 v26, 16, v22
	v_and_b32_e32 v27, 0xffff0000, v22
	v_lshlrev_b32_e32 v22, 16, v23
	v_and_b32_e32 v23, 0xffff0000, v23
	v_pk_mul_f32 v[22:23], v[50:51], v[22:23] op_sel:[1,0]
	v_lshlrev_b32_e32 v28, 16, v24
	v_pk_fma_f32 v[22:23], v[30:31], v[46:47], v[22:23] op_sel:[0,1,0]
	v_and_b32_e32 v29, 0xffff0000, v24
	v_lshlrev_b32_e32 v24, 16, v25
	v_and_b32_e32 v25, 0xffff0000, v25
	s_waitcnt vmcnt(14)
	v_lshlrev_b32_e32 v30, 16, v18
	v_and_b32_e32 v31, 0xffff0000, v18
	v_lshlrev_b32_e32 v18, 16, v19
	v_and_b32_e32 v19, 0xffff0000, v19
	v_pk_mul_f32 v[24:25], v[50:51], v[24:25] op_sel:[1,0]
	v_pk_mul_f32 v[18:19], v[50:51], v[18:19] op_sel:[1,0]
	v_pk_fma_f32 v[24:25], v[32:33], v[46:47], v[24:25] op_sel:[0,1,0]
	v_pk_fma_f32 v[32:33], v[42:43], v[46:47], v[18:19] op_sel:[0,1,0]
	v_lshlrev_b32_e32 v18, 16, v20
	v_and_b32_e32 v19, 0xffff0000, v20
	v_pk_mul_f32 v[26:27], v[50:51], v[26:27] op_sel:[1,0]
	v_pk_mul_f32 v[18:19], v[50:51], v[18:19] op_sel:[1,0]
	v_pk_fma_f32 v[26:27], v[34:35], v[46:47], v[26:27] op_sel:[0,1,0]
	v_pk_fma_f32 v[34:35], v[44:45], v[46:47], v[18:19] op_sel:[0,1,0]
	v_lshlrev_b32_e32 v18, 16, v21
	v_and_b32_e32 v19, 0xffff0000, v21
	v_pk_mul_f32 v[28:29], v[50:51], v[28:29] op_sel:[1,0]
	v_pk_mul_f32 v[18:19], v[50:51], v[18:19] op_sel:[1,0]
	v_pk_fma_f32 v[28:29], v[36:37], v[46:47], v[28:29] op_sel:[0,1,0]
	v_pk_mul_f32 v[30:31], v[50:51], v[30:31] op_sel:[1,0]
	v_pk_fma_f32 v[36:37], v[38:39], v[46:47], v[18:19] op_sel:[0,1,0]
	v_add_co_u32_e32 v38, vcc, s8, v86
	v_pk_fma_f32 v[30:31], v[40:41], v[46:47], v[30:31] op_sel:[0,1,0]
	v_cvt_pk_bf16_f32 v18, v26, v27
	v_cvt_pk_bf16_f32 v19, v22, v23
	v_cvt_pk_bf16_f32 v20, v28, v29
	v_cvt_pk_bf16_f32 v21, v24, v25
	v_addc_co_u32_e32 v39, vcc, 0, v87, vcc
	global_store_dwordx4 v[38:39], v[18:21], off
	s_mov_b32 s8, 0x27d60000
	s_nop 0
	v_cvt_pk_bf16_f32 v18, v30, v31
	v_cvt_pk_bf16_f32 v19, v32, v33
	v_cvt_pk_bf16_f32 v20, v34, v35
	v_cvt_pk_bf16_f32 v21, v36, v37
	global_store_dwordx4 v[38:39], v[18:21], off offset:512
	s_waitcnt vmcnt(15)
	s_nop 0
	v_lshlrev_b32_e32 v18, 16, v14
	v_and_b32_e32 v19, 0xffff0000, v14
	v_lshlrev_b32_e32 v14, 16, v15
	v_and_b32_e32 v15, 0xffff0000, v15
	v_pk_mul_f32 v[14:15], v[52:53], v[14:15] op_sel_hi:[0,1]
	v_pk_fma_f32 v[14:15], v[22:23], v[48:49], v[14:15] op_sel_hi:[1,0,1]
	v_lshlrev_b32_e32 v20, 16, v16
	v_and_b32_e32 v21, 0xffff0000, v16
	v_lshlrev_b32_e32 v16, 16, v17
	v_and_b32_e32 v17, 0xffff0000, v17
	s_waitcnt vmcnt(14)
	v_lshlrev_b32_e32 v22, 16, v10
	v_and_b32_e32 v23, 0xffff0000, v10
	v_lshlrev_b32_e32 v10, 16, v11
	v_and_b32_e32 v11, 0xffff0000, v11
	v_pk_mul_f32 v[16:17], v[52:53], v[16:17] op_sel_hi:[0,1]
	v_pk_mul_f32 v[10:11], v[52:53], v[10:11] op_sel_hi:[0,1]
	v_pk_fma_f32 v[16:17], v[24:25], v[48:49], v[16:17] op_sel_hi:[1,0,1]
	v_pk_fma_f32 v[24:25], v[32:33], v[48:49], v[10:11] op_sel_hi:[1,0,1]
	v_lshlrev_b32_e32 v10, 16, v12
	v_and_b32_e32 v11, 0xffff0000, v12
	v_pk_mul_f32 v[18:19], v[52:53], v[18:19] op_sel_hi:[0,1]
	v_pk_mul_f32 v[10:11], v[52:53], v[10:11] op_sel_hi:[0,1]
	v_pk_fma_f32 v[18:19], v[26:27], v[48:49], v[18:19] op_sel_hi:[1,0,1]
	v_pk_mul_f32 v[20:21], v[52:53], v[20:21] op_sel_hi:[0,1]
	v_pk_mul_f32 v[22:23], v[52:53], v[22:23] op_sel_hi:[0,1]
	v_pk_fma_f32 v[26:27], v[34:35], v[48:49], v[10:11] op_sel_hi:[1,0,1]
	v_lshlrev_b32_e32 v10, 16, v13
	v_and_b32_e32 v11, 0xffff0000, v13
	v_pk_fma_f32 v[20:21], v[28:29], v[48:49], v[20:21] op_sel_hi:[1,0,1]
	v_pk_fma_f32 v[22:23], v[30:31], v[48:49], v[22:23] op_sel_hi:[1,0,1]
	v_pk_mul_f32 v[10:11], v[52:53], v[10:11] op_sel_hi:[0,1]
	v_add_co_u32_e32 v30, vcc, s8, v86
	v_pk_fma_f32 v[28:29], v[36:37], v[48:49], v[10:11] op_sel_hi:[1,0,1]
	v_cvt_pk_bf16_f32 v10, v18, v19
	v_cvt_pk_bf16_f32 v11, v14, v15
	v_cvt_pk_bf16_f32 v12, v20, v21
	v_cvt_pk_bf16_f32 v13, v16, v17
	v_addc_co_u32_e32 v31, vcc, 0, v87, vcc
	global_store_dwordx4 v[30:31], v[10:13], off
	s_lshl_b64 s[8:9], s[0:1], 18
	s_add_u32 s8, s50, s8
	v_cvt_pk_bf16_f32 v10, v22, v23
	v_cvt_pk_bf16_f32 v11, v24, v25
	v_cvt_pk_bf16_f32 v12, v26, v27
	v_cvt_pk_bf16_f32 v13, v28, v29
	global_store_dwordx4 v[30:31], v[10:13], off offset:512
	s_addc_u32 s9, s51, s9
	s_lshl_b32 s6, s6, 7
	s_waitcnt vmcnt(15)
	v_lshlrev_b32_e32 v10, 16, v6
	v_lshlrev_b32_e32 v11, 16, v7
	v_mul_f32_e32 v10, v53, v10
	v_and_b32_e32 v6, 0xffff0000, v6
	v_mul_f32_e32 v11, v53, v11
	v_and_b32_e32 v7, 0xffff0000, v7
	v_fmac_f32_e32 v10, v18, v49
	v_mul_f32_e32 v6, v53, v6
	v_fmac_f32_e32 v11, v14, v49
	v_mul_f32_e32 v7, v53, v7
	v_lshlrev_b32_e32 v12, 16, v8
	v_and_b32_e32 v8, 0xffff0000, v8
	v_lshlrev_b32_e32 v13, 16, v9
	v_and_b32_e32 v9, 0xffff0000, v9
	s_waitcnt vmcnt(14)
	v_lshlrev_b32_e32 v14, 16, v2
	v_and_b32_e32 v2, 0xffff0000, v2
	v_mul_u32_u24_e32 v18, 0x84, v85
	v_fmac_f32_e32 v6, v19, v49
	v_fmac_f32_e32 v7, v15, v49
	v_mul_f32_e32 v12, v53, v12
	v_mul_f32_e32 v8, v53, v8
	v_mul_f32_e32 v13, v53, v13
	v_mul_f32_e32 v9, v53, v9
	v_mul_f32_e32 v2, v53, v2
	v_lshlrev_b32_e32 v15, 16, v3
	v_and_b32_e32 v3, 0xffff0000, v3
	v_add3_u32 v1, 0, v1, v18
	v_fmac_f32_e32 v12, v20, v49
	v_fmac_f32_e32 v8, v21, v49
	v_fmac_f32_e32 v13, v16, v49
	v_fmac_f32_e32 v9, v17, v49
	v_mul_f32_e32 v14, v53, v14
	v_fmac_f32_e32 v2, v23, v49
	v_mul_f32_e32 v15, v53, v15
	v_mul_f32_e32 v3, v53, v3
	v_lshlrev_b32_e32 v16, 16, v4
	v_and_b32_e32 v4, 0xffff0000, v4
	v_lshlrev_b32_e32 v17, 16, v5
	v_and_b32_e32 v5, 0xffff0000, v5
	ds_write2_b32 v1, v10, v6 offset0:128 offset1:161
	ds_write2_b32 v1, v11, v7 offset0:194 offset1:227
	v_add_u32_e32 v6, 0x400, v1
	v_fmac_f32_e32 v14, v22, v49
	v_fmac_f32_e32 v15, v24, v49
	v_fmac_f32_e32 v3, v25, v49
	v_mul_f32_e32 v16, v53, v16
	v_mul_f32_e32 v4, v53, v4
	v_mul_f32_e32 v5, v53, v5
	ds_write2_b32 v6, v12, v8 offset0:4 offset1:37
	ds_write2_b32 v6, v13, v9 offset0:70 offset1:103
	ds_write2_b32 v6, v14, v2 offset0:136 offset1:169
	ds_write2_b32 v6, v15, v3 offset0:202 offset1:235
	v_ashrrev_i32_e32 v2, 1, v84
	v_fmac_f32_e32 v16, v26, v49
	v_fmac_f32_e32 v4, v27, v49
	v_mul_f32_e32 v17, v53, v17
	v_fmac_f32_e32 v5, v29, v49
	v_add_u32_e32 v1, 0x800, v1
	v_ashrrev_i32_e32 v3, 31, v2
	v_fmac_f32_e32 v17, v28, v49
	ds_write2_b32 v1, v16, v4 offset0:12 offset1:45
	ds_write2_b32 v1, v17, v5 offset0:78 offset1:111
	v_lshlrev_b64 v[4:5], 10, v[2:3]
	v_lshlrev_b32_e32 v1, 6, v84
	v_lshl_add_u64 v[4:5], s[8:9], 0, v[4:5]
	v_and_b32_e32 v82, 64, v1
	v_mul_lo_u32 v1, v2, s10
	v_lshl_add_u64 v[4:5], v[4:5], 0, s[6:7]
	v_add3_u32 v1, 0, v1, v82
	s_waitcnt lgkmcnt(0)
	s_barrier
	v_lshl_add_u64 v[18:19], v[4:5], 0, v[82:83]
	s_mov_b64 s[6:7], 0x4080000
	s_mov_b32 s1, 0x4080000
	ds_read2_b32 v[2:3], v1 offset0:128 offset1:129
	ds_read2_b32 v[4:5], v1 offset0:130 offset1:131
	ds_read2_b32 v[6:7], v1 offset0:132 offset1:133
	ds_read2_b32 v[8:9], v1 offset0:134 offset1:135
	ds_read2_b32 v[10:11], v1 offset0:136 offset1:137
	ds_read2_b32 v[12:13], v1 offset0:138 offset1:139
	ds_read2_b32 v[14:15], v1 offset0:140 offset1:141
	ds_read2_b32 v[16:17], v1 offset0:142 offset1:143
	v_lshl_add_u64 v[20:21], v[18:19], 0, s[6:7]
	v_add_co_u32_e32 v18, vcc, s1, v18
	s_movk_i32 s1, 0x100
	s_nop 0
	v_addc_co_u32_e32 v19, vcc, 0, v19, vcc
	v_cmp_gt_i32_e32 vcc, s1, v84
	s_and_b64 s[6:7], s[2:3], vcc
	s_waitcnt lgkmcnt(6)
	global_store_dwordx4 v[18:19], v[2:5], off
	s_waitcnt lgkmcnt(4)
	global_store_dwordx4 v[20:21], v[6:9], off offset:16
	s_waitcnt lgkmcnt(2)
	global_store_dwordx4 v[20:21], v[10:13], off offset:32
	s_waitcnt lgkmcnt(0)
	global_store_dwordx4 v[20:21], v[14:17], off offset:48
	s_and_saveexec_b64 s[2:3], s[6:7]
	s_cbranch_execz .LBB0_958
	s_lshl_b64 s[4:5], s[4:5], 2
	v_ashrrev_i32_e32 v85, 31, v84
	s_add_u32 s4, s96, s4
	v_lshlrev_b64 v[2:3], 2, v[84:85]
	s_addc_u32 s5, s97, s5
	v_lshl_add_u64 v[4:5], s[4:5], 0, v[2:3]
	v_add_co_u32_e32 v8, vcc, 0x2bb80000, v4
	s_mov_b64 s[4:5], 0x2bb80000
	s_nop 0
	v_addc_co_u32_e32 v9, vcc, 0, v5, vcc
	v_add_co_u32_e32 v10, vcc, 0x2bb81000, v4
	v_lshl_add_u64 v[6:7], v[4:5], 0, s[4:5]
	s_nop 0
	v_addc_co_u32_e32 v11, vcc, 0, v5, vcc
	global_load_dword v23, v[8:9], off
	global_load_dword v1, v[6:7], off offset:1024
	global_load_dword v40, v[6:7], off offset:2048
	global_load_dword v41, v[10:11], off
	global_load_dword v42, v[10:11], off offset:1024
	global_load_dword v43, v[10:11], off offset:2048
	global_load_dword v44, v[10:11], off offset:3072
	global_load_dword v45, v[6:7], off offset:3072
	v_add_co_u32_e32 v24, vcc, 0x2bb82000, v4
	s_mov_b32 s1, 0x2bc01000
	s_nop 0
	v_addc_co_u32_e32 v25, vcc, 0, v5, vcc
	global_load_dword v46, v[24:25], off
	ds_read_b128 v[6:9], v83
	ds_read_b128 v[10:13], v83 offset:16
	ds_read_b128 v[14:17], v83 offset:64
	ds_read_b128 v[18:21], v83 offset:80
	global_load_dword v47, v[24:25], off offset:1024
	global_load_dword v48, v[24:25], off offset:2048
	global_load_dword v49, v[24:25], off offset:3072
	v_add_co_u32_e32 v28, vcc, s1, v4
	s_mov_b32 s6, 0x2bc02000
	s_nop 0
	v_addc_co_u32_e32 v29, vcc, 0, v5, vcc
	v_add_co_u32_e32 v30, vcc, s6, v4
	v_mov_b32_e32 v22, v83
	s_nop 0
	v_addc_co_u32_e32 v31, vcc, 0, v5, vcc
	v_add_co_u32_e32 v34, vcc, 0x2bb83000, v4
	s_waitcnt lgkmcnt(2)
	v_mov_b32_e32 v36, v10
	v_addc_co_u32_e32 v35, vcc, 0, v5, vcc
	global_load_dword v50, v[34:35], off
	global_load_dword v51, v[34:35], off offset:1024
	global_load_dword v52, v[34:35], off offset:2048
	global_load_dword v53, v[34:35], off offset:3072
	v_mov_b32_e32 v24, v6
	s_waitcnt lgkmcnt(1)
	v_mov_b32_e32 v25, v14
	s_mov_b64 s[4:5], 0x2bc00000
	v_lshl_add_u64 v[26:27], v[4:5], 0, s[4:5]
	v_mov_b32_e32 v32, v8
	v_mov_b32_e32 v33, v16
	s_waitcnt lgkmcnt(0)
	v_mov_b32_e32 v37, v18
	v_add_co_u32_e32 v38, vcc, 0x2bc00000, v4
	s_mov_b32 s1, 0x2bc03000
	s_nop 0
	v_addc_co_u32_e32 v39, vcc, 0, v5, vcc
	v_add_co_u32_e32 v4, vcc, s1, v4
	s_lshl_b32 s0, s0, 8
	s_nop 0
	v_addc_co_u32_e32 v5, vcc, 0, v5, vcc
	s_ashr_i32 s1, s0, 31
	s_lshl_b64 s[0:1], s[0:1], 2
	s_add_u32 s0, s50, s0
	s_addc_u32 s1, s51, s1
	v_lshl_add_u64 v[2:3], s[0:1], 0, v[2:3]
	v_add_co_u32_e32 v2, vcc, 0x4880000, v2
	global_store_dword v[38:39], v83, off
	s_nop 0
	v_addc_co_u32_e32 v3, vcc, 0, v3, vcc
	s_waitcnt vmcnt(16)
	v_mul_f32_e32 v10, v14, v23
	v_pk_fma_f32 v[22:23], v[24:25], v[22:23], v[10:11] op_sel_hi:[1,1,0]
	s_waitcnt vmcnt(15)
	v_mul_f32_e32 v6, v1, v15
	v_mov_b32_e32 v14, v7
	v_mov_b32_e32 v23, v1
	v_pk_fma_f32 v[6:7], v[22:23], v[14:15], v[6:7] op_sel_hi:[1,1,0]
	s_waitcnt vmcnt(14)
	v_mul_f32_e32 v8, v40, v16
	v_mov_b32_e32 v7, v40
	global_store_dword v[26:27], v6, off offset:2048
	v_pk_fma_f32 v[6:7], v[6:7], v[32:33], v[8:9] op_sel_hi:[1,1,0]
	v_mov_b32_e32 v16, v9
	s_waitcnt vmcnt(10)
	v_mul_f32_e32 v10, v45, v17
	v_mov_b32_e32 v7, v45
	global_store_dword v[26:27], v6, off offset:3072
	v_pk_fma_f32 v[6:7], v[6:7], v[16:17], v[10:11] op_sel_hi:[1,1,0]
	v_mul_f32_e32 v18, v41, v18
	v_mov_b32_e32 v7, v41
	global_store_dword v[30:31], v6, off offset:-4096
	v_pk_fma_f32 v[6:7], v[6:7], v[36:37], v[18:19] op_sel_hi:[1,1,0]
	v_mov_b32_e32 v18, v11
	v_mov_b32_e32 v7, v42
	v_mul_f32_e32 v8, v42, v19
	global_store_dword v[28:29], v6, off offset:1024
	v_pk_fma_f32 v[6:7], v[6:7], v[18:19], v[8:9] op_sel_hi:[1,1,0]
	v_mov_b32_e32 v8, v12
	v_mov_b32_e32 v7, v43
	v_mov_b32_e32 v9, v20
	v_mul_f32_e32 v10, v43, v20
	global_store_dword v[28:29], v6, off offset:2048
	v_pk_fma_f32 v[6:7], v[6:7], v[8:9], v[10:11] op_sel_hi:[1,1,0]
	v_mov_b32_e32 v20, v13
	v_mov_b32_e32 v7, v44
	v_mul_f32_e32 v8, v44, v21
	global_store_dword v[26:27], v22, off offset:1024
	global_store_dword v[28:29], v6, off offset:3072
	v_pk_fma_f32 v[22:23], v[6:7], v[20:21], v[8:9] op_sel_hi:[1,1,0]
	ds_read_b128 v[6:9], v83 offset:32
	ds_read_b128 v[14:17], v83 offset:48
	ds_read_b128 v[10:13], v83 offset:96
	ds_read_b128 v[18:21], v83 offset:112
	s_waitcnt vmcnt(15)
	v_mov_b32_e32 v23, v46
	s_waitcnt lgkmcnt(3)
	v_mov_b32_e32 v24, v6
	global_store_dword v[30:31], v22, off
	s_waitcnt lgkmcnt(1)
	v_mov_b32_e32 v25, v10
	v_mul_f32_e32 v6, v46, v10
	v_pk_fma_f32 v[22:23], v[22:23], v[24:25], v[6:7] op_sel_hi:[1,1,0]
	v_mov_b32_e32 v10, v7
	s_waitcnt vmcnt(15)
	v_mov_b32_e32 v23, v47
	v_mul_f32_e32 v6, v47, v11
	v_pk_fma_f32 v[6:7], v[22:23], v[10:11], v[6:7] op_sel_hi:[1,1,0]
	v_mov_b32_e32 v10, v8
	s_waitcnt vmcnt(14)
	v_mov_b32_e32 v7, v48
	v_mov_b32_e32 v11, v12
	v_mul_f32_e32 v8, v48, v12
	global_store_dword v[30:31], v6, off offset:2048
	v_pk_fma_f32 v[6:7], v[6:7], v[10:11], v[8:9] op_sel_hi:[1,1,0]
	v_mov_b32_e32 v12, v9
	s_waitcnt vmcnt(14)
	v_mov_b32_e32 v7, v49
	v_mul_f32_e32 v8, v49, v13
	global_store_dword v[30:31], v6, off offset:3072
	v_pk_fma_f32 v[6:7], v[6:7], v[12:13], v[8:9] op_sel_hi:[1,1,0]
	v_mov_b32_e32 v8, v14
	s_waitcnt vmcnt(14)
	v_mov_b32_e32 v7, v50
	s_waitcnt lgkmcnt(0)
	v_mov_b32_e32 v9, v18
	v_mul_f32_e32 v10, v50, v18
	global_store_dword v[4:5], v6, off
	v_pk_fma_f32 v[6:7], v[6:7], v[8:9], v[10:11] op_sel_hi:[1,1,0]
	v_mov_b32_e32 v18, v15
	s_waitcnt vmcnt(14)
	v_mov_b32_e32 v7, v51
	v_mul_f32_e32 v8, v51, v19
	global_store_dword v[4:5], v6, off offset:1024
	v_pk_fma_f32 v[6:7], v[6:7], v[18:19], v[8:9] op_sel_hi:[1,1,0]
	v_mov_b32_e32 v8, v16
	s_waitcnt vmcnt(14)
	v_mov_b32_e32 v7, v52
	v_mov_b32_e32 v9, v20
	v_mul_f32_e32 v10, v52, v20
	global_store_dword v[4:5], v6, off offset:2048
	v_pk_fma_f32 v[6:7], v[6:7], v[8:9], v[10:11] op_sel_hi:[1,1,0]
	v_mov_b32_e32 v20, v17
	s_waitcnt vmcnt(14)
	v_mov_b32_e32 v7, v53
	global_store_dword v[4:5], v6, off offset:3072
	v_pk_mul_f32 v[4:5], v[6:7], v[20:21]
	global_store_dword v[30:31], v22, off offset:1024
	v_add_f32_e32 v1, v4, v5
	global_store_dword v[2:3], v1, off
